# P5 and P8 hand-written residual epilogues writing to padded-stride (8320B) buffers (h2 in d_out scratch, h3 in dead MIX/HALO region); int8 row-quant pass, P8 residual and P9 read them
# speedup vs baseline: 1.0042x; 1.0002x over previous
; #define REPS(k) _Pragma("unroll") for (int rep_ = 0; rep_ <= ((DUP_MASK >> (k)) & 1); ++rep_)
;     __device__ bool next(int i, Unit& u) const {
;         const long L = (long)i * G + c; if (L >= nwg) return false;
;         int wgid = (int)L; { const int q = nwg / NXCD, r = nwg % NXCD, xcd = wgid % NXCD, off = wgid / NXCD; wgid = (xcd < r ? xcd * (q + 1) : r * (q + 1) + (xcd - r) * q) + off; }
;         const int nig = wgm * nN, gid = wgid / nig, fm = gid * wgm, gsz = (nM - fm) < wgm ? (nM - fm) : wgm;
;         u.pm = fm + ((wgid % nig) % gsz); u.pn = (wgid % nig) / gsz; u.z = 0; return true;
; __global__ void __launch_bounds__(NWAVES * 64, 2) fwd_kernel(Args args) {
;     ...
;     if (IN(5)) {
;         pg8::Gemm g{PB, VWO, NHEAD * MEMLEN, NHEAD * MEMLEN, NHEAD * MEMLEN, 1, SEQ / 256, 0, 0, 0, 0, (size_t)DM * NHEAD * MEMLEN}; pg8::StaticOrder S; S.init(MTOK / 256, DM / 256, G, bx);
;         REPS(5) { pg8::EpiResid<true> E{HB, rep_ ? (bf16*)dummy_out : HB, rep_ ? dummy_rsq : rsq2, rep_ ? (unsigned*)nullptr : rmaxU, DM, nullptr};
.LBB0_984:
	v_readlane_b32 s0, v244, 2
	v_readlane_b32 s14, v244, 16
	v_readlane_b32 s15, v244, 17
	s_add_u32 s56, s14, 0x85800
	s_addc_u32 s57, s15, 0
	s_add_u32 s54, s14, 0x50000
	s_addc_u32 s55, s15, 0
	v_readlane_b32 s1, v244, 3
	s_cmp_lt_i32 s96, 6
	v_readlane_b32 s2, v244, 4
	v_readlane_b32 s3, v244, 5
	s_cselect_b64 s[0:1], -1, 0
	s_cmp_gt_i32 s97, 5
	s_cselect_b64 s[2:3], -1, 0
	s_and_b64 s[0:1], s[0:1], s[2:3]
	s_andn2_b64 vcc, exec, s[0:1]
	v_readlane_b32 s4, v244, 6
	v_readlane_b32 s5, v244, 7
	v_readlane_b32 s6, v244, 8
	v_readlane_b32 s7, v244, 9
	v_readlane_b32 s8, v244, 10
	v_readlane_b32 s9, v244, 11
	v_readlane_b32 s10, v244, 12
	v_readlane_b32 s11, v244, 13
	v_readlane_b32 s12, v244, 14
	v_readlane_b32 s13, v244, 15
	s_cbranch_vccnz .LBB0_1177
	v_readlane_b32 s100, v244, 14
	v_readlane_b32 s101, v244, 15
	s_cmpk_lt_i32 s16, 0x400
	s_cselect_b64 s[0:1], -1, 0
	v_readfirstlane_b32 s10, v0
	s_lshr_b32 s11, s10, 6
	s_and_b64 vcc, exec, s[0:1]
	s_cbranch_vccz .LBB0_987
	s_ashr_i32 s2, s16, 31
	s_lshr_b32 s2, s2, 29
	s_add_i32 s2, s16, s2
	s_and_b32 s3, s2, -8
	s_sub_i32 s3, s16, s3
	s_lshl_b32 s5, s3, 7
	s_ashr_i32 s2, s2, 3
	s_mul_i32 s4, s3, 0x81
	s_cmp_lt_i32 s3, 0
	s_cselect_b32 s3, s4, s5
	s_add_i32 s2, s3, s2
	s_ashr_i32 s3, s2, 31
	s_lshr_b32 s3, s3, 25
	s_add_i32 s3, s2, s3
	s_ashr_i32 s4, s3, 7
	s_and_b32 s3, s3, 0xffffff80
	s_sub_i32 s2, s2, s3
	s_bfe_i32 s3, s2, 0x80000
	s_bfe_u32 s3, s3, 0x3000c
	s_add_i32 s3, s2, s3
	s_bfe_i32 s5, s3, 0x80000
	s_and_b32 s3, s3, 0xf8
	s_sub_i32 s2, s2, s3
	s_lshl_b32 s4, s4, 3
	s_sext_i32_i16 s5, s5
	s_sext_i32_i8 s2, s2
	s_add_i32 s72, s4, s2
	s_ashr_i32 s70, s5, 3

; __device__ __forceinline__ unsigned cvt_pk_bf16(float lo, float hi) { unsigned r; asm volatile("v_cvt_pk_bf16_f32 %0, %1, %2" : "=v"(r) : "v"(lo), "v"(hi)); return r; }
; __device__ __forceinline__ float bf_lo(unsigned w) { return __uint_as_float(w << 16); }
;     __device__ __forceinline__ void operator()(EPI_ARGS) const {
;         const int row0 = u.pm * BM + wr * 64 + fr, col0 = u.pn * BM + wc * 32 + 8 * fq;
;         float ssv[8], mxv[8];
; #pragma unroll
;         for (int ai = 0; ai < 2; ++ai) {
;             f32x4 r0[4][2], r1[4][2];
; #pragma unroll
;             for (int m = 0; m < 4; ++m)
; #pragma unroll
;                 for (int bj = 0; bj < 2; ++bj) { const size_t off = (size_t)(row0 + ai * HALF + m * 16) * ldc + col0 + bj * HALF;
;                     if (RES_BF16) { const u32x4 rw = *(const u32x4*)((const bf16*)resid + off); r0[m][bj] = __builtin_bit_cast(f32x4, rw); }
;                     else { r0[m][bj] = *(const f32x4*)((const float*)resid + off); r1[m][bj] = *(const f32x4*)((const float*)resid + off + 4); } }
; #pragma unroll
;             for (int m = 0; m < 4; ++m) { const int row = row0 + ai * HALF + m * 16; const size_t off = (size_t)row * ldc + col0; float ss = 0.f, mx = 0.f;
; #pragma unroll
;                 for (int bj = 0; bj < 2; ++bj) {
;                     f32x4 a0, a1;
;                     if (RES_BF16) { const u32x4 rw = __builtin_bit_cast(u32x4, r0[m][bj]); a0 = (f32x4){bf_lo(rw.x), bf_hi(rw.x), bf_lo(rw.y), bf_hi(rw.y)}; a1 = (f32x4){bf_lo(rw.z), bf_hi(rw.z), bf_lo(rw.w), bf_hi(rw.w)};
;                         if (RES_SCALE) { const float rf = rfac[row]; a0 = a0 * rf; a1 = a1 * rf; } }
;                     else { a0 = r0[m][bj]; a1 = r1[m][bj]; }
;                     const f32x4 v0 = acc[ai][bj][m][0] + a0, v1 = acc[ai][bj][m][1] + a1;
;                     u32x4 w; w.x = cvt_pk_bf16(v0[0], v0[1]); w.y = cvt_pk_bf16(v0[2], v0[3]); w.z = cvt_pk_bf16(v1[0], v1[1]); w.w = cvt_pk_bf16(v1[2], v1[3]); *(u32x4*)(ob + off + bj * HALF) = w;
;                     ss += (v0[0] * v0[0] + v0[1] * v0[1]) + (v0[2] * v0[2] + v0[3] * v0[3]) + (v1[0] * v1[0] + v1[1] * v1[1]) + (v1[2] * v1[2] + v1[3] * v1[3]);
;                     if (rowmax) mx = fmaxf(mx, fmaxf(fmaxf(fmaxf(fabsf(v0[0]), fabsf(v0[1])), fmaxf(fabsf(v0[2]), fabsf(v0[3]))), fmaxf(fmaxf(fabsf(v1[0]), fabsf(v1[1])), fmaxf(fabsf(v1[2]), fabsf(v1[3]))))); }
.LBB0_1005:
	s_nop 7
	v_lshl_add_u32 v245, s72, 8, v181
	v_lshlrev_b32_e32 v245, 13, v245
	v_lshl_or_b32 v246, s70, 8, v182
	v_lshl_add_u32 v245, v246, 1, v245
	global_load_dwordx4 v[130:133], v245, s[52:53]
	global_load_dwordx4 v[134:137], v245, s[52:53] offset:256
	v_add_u32_e32 v246, 0x20000, v245
	global_load_dwordx4 v[138:141], v246, s[52:53]
	global_load_dwordx4 v[142:145], v246, s[52:53] offset:256
	v_add_u32_e32 v255, 0x40000, v245
	global_load_dwordx4 v[146:149], v255, s[52:53]
	global_load_dwordx4 v[150:153], v255, s[52:53] offset:256
	v_add_u32_e32 v246, 0x60000, v245
	global_load_dwordx4 v[154:157], v246, s[52:53]
	global_load_dwordx4 v[162:165], v246, s[52:53] offset:256
	v_add_u32_e32 v255, 0x100000, v245
	global_load_dwordx4 v[166:169], v255, s[52:53]
	global_load_dwordx4 v[170:173], v255, s[52:53] offset:256
	v_add_u32_e32 v246, 0x120000, v245
	global_load_dwordx4 v[190:193], v246, s[52:53]
	global_load_dwordx4 v[194:197], v246, s[52:53] offset:256
	v_add_u32_e32 v255, 0x140000, v245
	global_load_dwordx4 v[198:201], v255, s[52:53]
	global_load_dwordx4 v[202:205], v255, s[52:53] offset:256
	v_add_u32_e32 v246, 0x160000, v245
	global_load_dwordx4 v[206:209], v246, s[52:53]
	global_load_dwordx4 v[210:213], v246, s[52:53] offset:256
	v_lshl_add_u32 v245, s72, 8, v181
	v_mul_u32_u24_e32 v245, 0x2080, v245
	v_lshl_or_b32 v246, s70, 8, v182
	v_lshl_add_u32 v245, v246, 1, v245
	s_waitcnt vmcnt(15)
	v_lshlrev_b32_e32 v248, 16, v130
	v_and_b32_e32 v249, 0xffff0000, v130
	v_lshlrev_b32_e32 v250, 16, v131
	v_and_b32_e32 v251, 0xffff0000, v131
	v_pk_add_f32 v[126:127], v[126:127], v[248:249]
	v_pk_add_f32 v[128:129], v[128:129], v[250:251]
	v_lshlrev_b32_e32 v248, 16, v132
	v_and_b32_e32 v249, 0xffff0000, v132
	v_lshlrev_b32_e32 v250, 16, v133
	v_and_b32_e32 v251, 0xffff0000, v133
	v_pk_add_f32 v[122:123], v[122:123], v[248:249]
	v_pk_add_f32 v[124:125], v[124:125], v[250:251]
	v_cvt_pk_bf16_f32 v130, v126, v127
	v_cvt_pk_bf16_f32 v131, v128, v129
	v_cvt_pk_bf16_f32 v132, v122, v123
	v_cvt_pk_bf16_f32 v133, v124, v125
	global_store_dwordx4 v245, v[130:133], s[100:101]
	v_mul_f32_e32 v247, v126, v126
	v_fmac_f32_e32 v247, v127, v127
	v_fmac_f32_e32 v247, v128, v128
	v_fmac_f32_e32 v247, v129, v129
	v_mul_f32_e32 v254, v122, v122
	v_fmac_f32_e32 v254, v123, v123
	v_fmac_f32_e32 v254, v124, v124
	v_fmac_f32_e32 v254, v125, v125
	v_max3_f32 v252, |v126|, |v127|, |v128|
	v_max3_f32 v252, |v129|, |v122|, v252
	v_max3_f32 v252, |v123|, |v124|, v252
	v_max_f32_e64 v252, |v125|, v252
	s_waitcnt vmcnt(15)
	v_lshlrev_b32_e32 v248, 16, v134
	v_and_b32_e32 v249, 0xffff0000, v134
	v_lshlrev_b32_e32 v250, 16, v135
	v_and_b32_e32 v251, 0xffff0000, v135
	v_pk_add_f32 v[118:119], v[118:119], v[248:249]
	v_pk_add_f32 v[120:121], v[120:121], v[250:251]
	v_lshlrev_b32_e32 v248, 16, v136
	v_and_b32_e32 v249, 0xffff0000, v136
	v_lshlrev_b32_e32 v250, 16, v137
	v_and_b32_e32 v251, 0xffff0000, v137
	v_pk_add_f32 v[114:115], v[114:115], v[248:249]
	v_pk_add_f32 v[116:117], v[116:117], v[250:251]
	v_cvt_pk_bf16_f32 v134, v118, v119
	v_cvt_pk_bf16_f32 v135, v120, v121
	v_cvt_pk_bf16_f32 v136, v114, v115
	v_cvt_pk_bf16_f32 v137, v116, v117
	global_store_dwordx4 v245, v[134:137], s[100:101] offset:256
	v_fmac_f32_e32 v247, v118, v118
	v_fmac_f32_e32 v247, v119, v119
	v_fmac_f32_e32 v247, v120, v120
	v_fmac_f32_e32 v247, v121, v121
	v_fmac_f32_e32 v254, v114, v114
	v_fmac_f32_e32 v254, v115, v115
	v_fmac_f32_e32 v254, v116, v116
	v_fmac_f32_e32 v254, v117, v117
	v_max3_f32 v252, |v118|, |v119|, v252
	v_max_f32_e64 v252, |v120|, v252
	v_max3_f32 v252, |v121|, |v114|, v252
	v_max3_f32 v252, |v115|, |v116|, v252
	v_max_f32_e64 v252, |v117|, v252
	v_add_f32_e32 v126, v247, v254
	v_mov_b32_e32 v128, v252
	s_waitcnt vmcnt(15)
	v_lshlrev_b32_e32 v248, 16, v138
	v_and_b32_e32 v249, 0xffff0000, v138
	v_lshlrev_b32_e32 v250, 16, v139
	v_and_b32_e32 v251, 0xffff0000, v139
	v_pk_add_f32 v[110:111], v[110:111], v[248:249]
	v_pk_add_f32 v[112:113], v[112:113], v[250:251]
	v_lshlrev_b32_e32 v248, 16, v140
	v_and_b32_e32 v249, 0xffff0000, v140
	v_lshlrev_b32_e32 v250, 16, v141
	v_and_b32_e32 v251, 0xffff0000, v141
	v_pk_add_f32 v[106:107], v[106:107], v[248:249]
	v_pk_add_f32 v[108:109], v[108:109], v[250:251]
	v_cvt_pk_bf16_f32 v138, v110, v111
	v_cvt_pk_bf16_f32 v139, v112, v113
	v_cvt_pk_bf16_f32 v140, v106, v107
	v_cvt_pk_bf16_f32 v141, v108, v109
	v_add_u32_e32 v246, 0x20800, v245
	global_store_dwordx4 v246, v[138:141], s[100:101]
	v_mul_f32_e32 v247, v110, v110
	v_fmac_f32_e32 v247, v111, v111
	v_fmac_f32_e32 v247, v112, v112
	v_fmac_f32_e32 v247, v113, v113
	v_mul_f32_e32 v254, v106, v106
	v_fmac_f32_e32 v254, v107, v107
	v_fmac_f32_e32 v254, v108, v108
	v_fmac_f32_e32 v254, v109, v109
	v_max3_f32 v252, |v110|, |v111|, |v112|
	v_max3_f32 v252, |v113|, |v106|, v252
	v_max3_f32 v252, |v107|, |v108|, v252
	v_max_f32_e64 v252, |v109|, v252
	s_waitcnt vmcnt(15)
	v_lshlrev_b32_e32 v248, 16, v142
	v_and_b32_e32 v249, 0xffff0000, v142
	v_lshlrev_b32_e32 v250, 16, v143
	v_and_b32_e32 v251, 0xffff0000, v143
	v_pk_add_f32 v[102:103], v[102:103], v[248:249]
	v_pk_add_f32 v[104:105], v[104:105], v[250:251]
	v_lshlrev_b32_e32 v248, 16, v144
	v_and_b32_e32 v249, 0xffff0000, v144
	v_lshlrev_b32_e32 v250, 16, v145
	v_and_b32_e32 v251, 0xffff0000, v145
	v_pk_add_f32 v[98:99], v[98:99], v[248:249]
	v_pk_add_f32 v[100:101], v[100:101], v[250:251]
	v_cvt_pk_bf16_f32 v142, v102, v103
	v_cvt_pk_bf16_f32 v143, v104, v105
	v_cvt_pk_bf16_f32 v144, v98, v99
	v_cvt_pk_bf16_f32 v145, v100, v101
	v_add_u32_e32 v255, 0x20800, v245
	global_store_dwordx4 v255, v[142:145], s[100:101] offset:256
	v_fmac_f32_e32 v247, v102, v102
	v_fmac_f32_e32 v247, v103, v103
	v_fmac_f32_e32 v247, v104, v104
	v_fmac_f32_e32 v247, v105, v105
	v_fmac_f32_e32 v254, v98, v98
	v_fmac_f32_e32 v254, v99, v99
	v_fmac_f32_e32 v254, v100, v100
	v_fmac_f32_e32 v254, v101, v101
	v_max3_f32 v252, |v102|, |v103|, v252
	v_max_f32_e64 v252, |v104|, v252
	v_max3_f32 v252, |v105|, |v98|, v252
	v_max3_f32 v252, |v99|, |v100|, v252
	v_max_f32_e64 v252, |v101|, v252
	v_add_f32_e32 v110, v247, v254
	v_mov_b32_e32 v112, v252
	s_waitcnt vmcnt(15)
; __device__ __forceinline__ unsigned cvt_pk_bf16(float lo, float hi) { unsigned r; asm volatile("v_cvt_pk_bf16_f32 %0, %1, %2" : "=v"(r) : "v"(lo), "v"(hi)); return r; }
; __device__ __forceinline__ float bf_lo(unsigned w) { return __uint_as_float(w << 16); }
; __device__ __forceinline__ float bf_hi(unsigned w) { return __uint_as_float(w & 0xffff0000u); }
;     __device__ __forceinline__ void operator()(EPI_ARGS) const {
;     ...
;                 for (int bj = 0; bj < 2; ++bj) { const size_t off = (size_t)(row0 + ai * HALF + m * 16) * ldc + col0 + bj * HALF;
;                     if (RES_BF16) { const u32x4 rw = *(const u32x4*)((const bf16*)resid + off); r0[m][bj] = __builtin_bit_cast(f32x4, rw); }
;                     else { r0[m][bj] = *(const f32x4*)((const float*)resid + off); r1[m][bj] = *(const f32x4*)((const float*)resid + off + 4); } }
; #pragma unroll
;             for (int m = 0; m < 4; ++m) { const int row = row0 + ai * HALF + m * 16; const size_t off = (size_t)row * ldc + col0; float ss = 0.f, mx = 0.f;
; #pragma unroll
;                 for (int bj = 0; bj < 2; ++bj) {
;                     f32x4 a0, a1;
;                     if (RES_BF16) { const u32x4 rw = __builtin_bit_cast(u32x4, r0[m][bj]); a0 = (f32x4){bf_lo(rw.x), bf_hi(rw.x), bf_lo(rw.y), bf_hi(rw.y)}; a1 = (f32x4){bf_lo(rw.z), bf_hi(rw.z), bf_lo(rw.w), bf_hi(rw.w)};
;                         if (RES_SCALE) { const float rf = rfac[row]; a0 = a0 * rf; a1 = a1 * rf; } }
;                     else { a0 = r0[m][bj]; a1 = r1[m][bj]; }
;                     const f32x4 v0 = acc[ai][bj][m][0] + a0, v1 = acc[ai][bj][m][1] + a1;
;                     u32x4 w; w.x = cvt_pk_bf16(v0[0], v0[1]); w.y = cvt_pk_bf16(v0[2], v0[3]); w.z = cvt_pk_bf16(v1[0], v1[1]); w.w = cvt_pk_bf16(v1[2], v1[3]); *(u32x4*)(ob + off + bj * HALF) = w;
;                     ss += (v0[0] * v0[0] + v0[1] * v0[1]) + (v0[2] * v0[2] + v0[3] * v0[3]) + (v1[0] * v1[0] + v1[1] * v1[1]) + (v1[2] * v1[2] + v1[3] * v1[3]);
;                     if (rowmax) mx = fmaxf(mx, fmaxf(fmaxf(fmaxf(fabsf(v0[0]), fabsf(v0[1])), fmaxf(fabsf(v0[2]), fabsf(v0[3]))), fmaxf(fmaxf(fabsf(v1[0]), fabsf(v1[1])), fmaxf(fabsf(v1[2]), fabsf(v1[3]))))); }
	v_lshlrev_b32_e32 v248, 16, v146
	v_and_b32_e32 v249, 0xffff0000, v146
	v_lshlrev_b32_e32 v250, 16, v147
	v_and_b32_e32 v251, 0xffff0000, v147
	v_pk_add_f32 v[94:95], v[94:95], v[248:249]
	v_pk_add_f32 v[96:97], v[96:97], v[250:251]
	v_lshlrev_b32_e32 v248, 16, v148
	v_and_b32_e32 v249, 0xffff0000, v148
	v_lshlrev_b32_e32 v250, 16, v149
	v_and_b32_e32 v251, 0xffff0000, v149
	v_pk_add_f32 v[90:91], v[90:91], v[248:249]
	v_pk_add_f32 v[92:93], v[92:93], v[250:251]
	v_cvt_pk_bf16_f32 v146, v94, v95
	v_cvt_pk_bf16_f32 v147, v96, v97
	v_cvt_pk_bf16_f32 v148, v90, v91
	v_cvt_pk_bf16_f32 v149, v92, v93
	v_add_u32_e32 v246, 0x41000, v245
	global_store_dwordx4 v246, v[146:149], s[100:101]
	v_mul_f32_e32 v247, v94, v94
	v_fmac_f32_e32 v247, v95, v95
	v_fmac_f32_e32 v247, v96, v96
	v_fmac_f32_e32 v247, v97, v97
	v_mul_f32_e32 v254, v90, v90
	v_fmac_f32_e32 v254, v91, v91
	v_fmac_f32_e32 v254, v92, v92
	v_fmac_f32_e32 v254, v93, v93
	v_max3_f32 v252, |v94|, |v95|, |v96|
	v_max3_f32 v252, |v97|, |v90|, v252
	v_max3_f32 v252, |v91|, |v92|, v252
	v_max_f32_e64 v252, |v93|, v252
	s_waitcnt vmcnt(15)
	v_lshlrev_b32_e32 v248, 16, v150
	v_and_b32_e32 v249, 0xffff0000, v150
	v_lshlrev_b32_e32 v250, 16, v151
	v_and_b32_e32 v251, 0xffff0000, v151
	v_pk_add_f32 v[86:87], v[86:87], v[248:249]
	v_pk_add_f32 v[88:89], v[88:89], v[250:251]
	v_lshlrev_b32_e32 v248, 16, v152
	v_and_b32_e32 v249, 0xffff0000, v152
	v_lshlrev_b32_e32 v250, 16, v153
	v_and_b32_e32 v251, 0xffff0000, v153
	v_pk_add_f32 v[82:83], v[82:83], v[248:249]
	v_pk_add_f32 v[84:85], v[84:85], v[250:251]
	v_cvt_pk_bf16_f32 v150, v86, v87
	v_cvt_pk_bf16_f32 v151, v88, v89
	v_cvt_pk_bf16_f32 v152, v82, v83
	v_cvt_pk_bf16_f32 v153, v84, v85
	v_add_u32_e32 v255, 0x41000, v245
	global_store_dwordx4 v255, v[150:153], s[100:101] offset:256
	v_fmac_f32_e32 v247, v86, v86
	v_fmac_f32_e32 v247, v87, v87
	v_fmac_f32_e32 v247, v88, v88
	v_fmac_f32_e32 v247, v89, v89
	v_fmac_f32_e32 v254, v82, v82
	v_fmac_f32_e32 v254, v83, v83
	v_fmac_f32_e32 v254, v84, v84
	v_fmac_f32_e32 v254, v85, v85
	v_max3_f32 v252, |v86|, |v87|, v252
	v_max_f32_e64 v252, |v88|, v252
	v_max3_f32 v252, |v89|, |v82|, v252
	v_max3_f32 v252, |v83|, |v84|, v252
	v_max_f32_e64 v252, |v85|, v252
	v_add_f32_e32 v94, v247, v254
	v_mov_b32_e32 v96, v252
	s_waitcnt vmcnt(15)
	v_lshlrev_b32_e32 v248, 16, v154
	v_and_b32_e32 v249, 0xffff0000, v154
	v_lshlrev_b32_e32 v250, 16, v155
	v_and_b32_e32 v251, 0xffff0000, v155
	v_pk_add_f32 v[78:79], v[78:79], v[248:249]
	v_pk_add_f32 v[80:81], v[80:81], v[250:251]
	v_lshlrev_b32_e32 v248, 16, v156
	v_and_b32_e32 v249, 0xffff0000, v156
	v_lshlrev_b32_e32 v250, 16, v157
	v_and_b32_e32 v251, 0xffff0000, v157
	v_pk_add_f32 v[74:75], v[74:75], v[248:249]
	v_pk_add_f32 v[76:77], v[76:77], v[250:251]
	v_cvt_pk_bf16_f32 v154, v78, v79
	v_cvt_pk_bf16_f32 v155, v80, v81
	v_cvt_pk_bf16_f32 v156, v74, v75
	v_cvt_pk_bf16_f32 v157, v76, v77
	v_add_u32_e32 v246, 0x61800, v245
	global_store_dwordx4 v246, v[154:157], s[100:101]
	v_mul_f32_e32 v247, v78, v78
	v_fmac_f32_e32 v247, v79, v79
	v_fmac_f32_e32 v247, v80, v80
	v_fmac_f32_e32 v247, v81, v81
	v_mul_f32_e32 v254, v74, v74
	v_fmac_f32_e32 v254, v75, v75
	v_fmac_f32_e32 v254, v76, v76
	v_fmac_f32_e32 v254, v77, v77
	v_max3_f32 v252, |v78|, |v79|, |v80|
	v_max3_f32 v252, |v81|, |v74|, v252
	v_max3_f32 v252, |v75|, |v76|, v252
	v_max_f32_e64 v252, |v77|, v252
	s_waitcnt vmcnt(15)
	v_lshlrev_b32_e32 v248, 16, v162
	v_and_b32_e32 v249, 0xffff0000, v162
	v_lshlrev_b32_e32 v250, 16, v163
	v_and_b32_e32 v251, 0xffff0000, v163
	v_pk_add_f32 v[70:71], v[70:71], v[248:249]
	v_pk_add_f32 v[72:73], v[72:73], v[250:251]
	v_lshlrev_b32_e32 v248, 16, v164
	v_and_b32_e32 v249, 0xffff0000, v164
	v_lshlrev_b32_e32 v250, 16, v165
	v_and_b32_e32 v251, 0xffff0000, v165
	v_pk_add_f32 v[66:67], v[66:67], v[248:249]
	v_pk_add_f32 v[68:69], v[68:69], v[250:251]
	v_cvt_pk_bf16_f32 v162, v70, v71
	v_cvt_pk_bf16_f32 v163, v72, v73
	v_cvt_pk_bf16_f32 v164, v66, v67
	v_cvt_pk_bf16_f32 v165, v68, v69
	v_add_u32_e32 v255, 0x61800, v245
	global_store_dwordx4 v255, v[162:165], s[100:101] offset:256
	v_fmac_f32_e32 v247, v70, v70
	v_fmac_f32_e32 v247, v71, v71
	v_fmac_f32_e32 v247, v72, v72
	v_fmac_f32_e32 v247, v73, v73
	v_fmac_f32_e32 v254, v66, v66
	v_fmac_f32_e32 v254, v67, v67
	v_fmac_f32_e32 v254, v68, v68
	v_fmac_f32_e32 v254, v69, v69
	v_max3_f32 v252, |v70|, |v71|, v252
	v_max_f32_e64 v252, |v72|, v252
	v_max3_f32 v252, |v73|, |v66|, v252
	v_max3_f32 v252, |v67|, |v68|, v252
	v_max_f32_e64 v252, |v69|, v252
	v_add_f32_e32 v78, v247, v254
	v_mov_b32_e32 v80, v252
	s_waitcnt vmcnt(15)
	v_lshlrev_b32_e32 v248, 16, v166
	v_and_b32_e32 v249, 0xffff0000, v166
	v_lshlrev_b32_e32 v250, 16, v167
	v_and_b32_e32 v251, 0xffff0000, v167
	v_pk_add_f32 v[62:63], v[62:63], v[248:249]
	v_pk_add_f32 v[64:65], v[64:65], v[250:251]
	v_lshlrev_b32_e32 v248, 16, v168
	v_and_b32_e32 v249, 0xffff0000, v168
	v_lshlrev_b32_e32 v250, 16, v169
	v_and_b32_e32 v251, 0xffff0000, v169
	v_pk_add_f32 v[58:59], v[58:59], v[248:249]
	v_pk_add_f32 v[60:61], v[60:61], v[250:251]
	v_cvt_pk_bf16_f32 v166, v62, v63
	v_cvt_pk_bf16_f32 v167, v64, v65
	v_cvt_pk_bf16_f32 v168, v58, v59
	v_cvt_pk_bf16_f32 v169, v60, v61
	v_add_u32_e32 v246, 0x104000, v245
	global_store_dwordx4 v246, v[166:169], s[100:101]
	v_mul_f32_e32 v247, v62, v62
	v_fmac_f32_e32 v247, v63, v63
	v_fmac_f32_e32 v247, v64, v64
	v_fmac_f32_e32 v247, v65, v65
	v_mul_f32_e32 v254, v58, v58
	v_fmac_f32_e32 v254, v59, v59
	v_fmac_f32_e32 v254, v60, v60
	v_fmac_f32_e32 v254, v61, v61
	v_max3_f32 v252, |v62|, |v63|, |v64|
	v_max3_f32 v252, |v65|, |v58|, v252
	v_max3_f32 v252, |v59|, |v60|, v252
	v_max_f32_e64 v252, |v61|, v252
	s_waitcnt vmcnt(15)
; __device__ __forceinline__ unsigned cvt_pk_bf16(float lo, float hi) { unsigned r; asm volatile("v_cvt_pk_bf16_f32 %0, %1, %2" : "=v"(r) : "v"(lo), "v"(hi)); return r; }
; __device__ __forceinline__ float bf_lo(unsigned w) { return __uint_as_float(w << 16); }
; __device__ __forceinline__ float bf_hi(unsigned w) { return __uint_as_float(w & 0xffff0000u); }
;     __device__ __forceinline__ void operator()(EPI_ARGS) const {
;     ...
;                 for (int bj = 0; bj < 2; ++bj) { const size_t off = (size_t)(row0 + ai * HALF + m * 16) * ldc + col0 + bj * HALF;
;                     if (RES_BF16) { const u32x4 rw = *(const u32x4*)((const bf16*)resid + off); r0[m][bj] = __builtin_bit_cast(f32x4, rw); }
;                     else { r0[m][bj] = *(const f32x4*)((const float*)resid + off); r1[m][bj] = *(const f32x4*)((const float*)resid + off + 4); } }
; #pragma unroll
;             for (int m = 0; m < 4; ++m) { const int row = row0 + ai * HALF + m * 16; const size_t off = (size_t)row * ldc + col0; float ss = 0.f, mx = 0.f;
; #pragma unroll
;                 for (int bj = 0; bj < 2; ++bj) {
;                     f32x4 a0, a1;
;                     if (RES_BF16) { const u32x4 rw = __builtin_bit_cast(u32x4, r0[m][bj]); a0 = (f32x4){bf_lo(rw.x), bf_hi(rw.x), bf_lo(rw.y), bf_hi(rw.y)}; a1 = (f32x4){bf_lo(rw.z), bf_hi(rw.z), bf_lo(rw.w), bf_hi(rw.w)};
;                         if (RES_SCALE) { const float rf = rfac[row]; a0 = a0 * rf; a1 = a1 * rf; } }
;                     else { a0 = r0[m][bj]; a1 = r1[m][bj]; }
;                     const f32x4 v0 = acc[ai][bj][m][0] + a0, v1 = acc[ai][bj][m][1] + a1;
;                     u32x4 w; w.x = cvt_pk_bf16(v0[0], v0[1]); w.y = cvt_pk_bf16(v0[2], v0[3]); w.z = cvt_pk_bf16(v1[0], v1[1]); w.w = cvt_pk_bf16(v1[2], v1[3]); *(u32x4*)(ob + off + bj * HALF) = w;
;                     ss += (v0[0] * v0[0] + v0[1] * v0[1]) + (v0[2] * v0[2] + v0[3] * v0[3]) + (v1[0] * v1[0] + v1[1] * v1[1]) + (v1[2] * v1[2] + v1[3] * v1[3]);
;                     if (rowmax) mx = fmaxf(mx, fmaxf(fmaxf(fmaxf(fabsf(v0[0]), fabsf(v0[1])), fmaxf(fabsf(v0[2]), fabsf(v0[3]))), fmaxf(fmaxf(fabsf(v1[0]), fabsf(v1[1])), fmaxf(fabsf(v1[2]), fabsf(v1[3]))))); }
	v_lshlrev_b32_e32 v248, 16, v170
	v_and_b32_e32 v249, 0xffff0000, v170
	v_lshlrev_b32_e32 v250, 16, v171
	v_and_b32_e32 v251, 0xffff0000, v171
	v_pk_add_f32 v[54:55], v[54:55], v[248:249]
	v_pk_add_f32 v[56:57], v[56:57], v[250:251]
	v_lshlrev_b32_e32 v248, 16, v172
	v_and_b32_e32 v249, 0xffff0000, v172
	v_lshlrev_b32_e32 v250, 16, v173
	v_and_b32_e32 v251, 0xffff0000, v173
	v_pk_add_f32 v[50:51], v[50:51], v[248:249]
	v_pk_add_f32 v[52:53], v[52:53], v[250:251]
	v_cvt_pk_bf16_f32 v170, v54, v55
	v_cvt_pk_bf16_f32 v171, v56, v57
	v_cvt_pk_bf16_f32 v172, v50, v51
	v_cvt_pk_bf16_f32 v173, v52, v53
	v_add_u32_e32 v255, 0x104000, v245
	global_store_dwordx4 v255, v[170:173], s[100:101] offset:256
	v_fmac_f32_e32 v247, v54, v54
	v_fmac_f32_e32 v247, v55, v55
	v_fmac_f32_e32 v247, v56, v56
	v_fmac_f32_e32 v247, v57, v57
	v_fmac_f32_e32 v254, v50, v50
	v_fmac_f32_e32 v254, v51, v51
	v_fmac_f32_e32 v254, v52, v52
	v_fmac_f32_e32 v254, v53, v53
	v_max3_f32 v252, |v54|, |v55|, v252
	v_max_f32_e64 v252, |v56|, v252
	v_max3_f32 v252, |v57|, |v50|, v252
	v_max3_f32 v252, |v51|, |v52|, v252
	v_max_f32_e64 v252, |v53|, v252
	v_add_f32_e32 v62, v247, v254
	v_mov_b32_e32 v64, v252
	s_waitcnt vmcnt(15)
	v_lshlrev_b32_e32 v248, 16, v190
	v_and_b32_e32 v249, 0xffff0000, v190
	v_lshlrev_b32_e32 v250, 16, v191
	v_and_b32_e32 v251, 0xffff0000, v191
	v_pk_add_f32 v[46:47], v[46:47], v[248:249]
	v_pk_add_f32 v[48:49], v[48:49], v[250:251]
	v_lshlrev_b32_e32 v248, 16, v192
	v_and_b32_e32 v249, 0xffff0000, v192
	v_lshlrev_b32_e32 v250, 16, v193
	v_and_b32_e32 v251, 0xffff0000, v193
	v_pk_add_f32 v[42:43], v[42:43], v[248:249]
	v_pk_add_f32 v[44:45], v[44:45], v[250:251]
	v_cvt_pk_bf16_f32 v190, v46, v47
	v_cvt_pk_bf16_f32 v191, v48, v49
	v_cvt_pk_bf16_f32 v192, v42, v43
	v_cvt_pk_bf16_f32 v193, v44, v45
	v_add_u32_e32 v246, 0x124800, v245
	global_store_dwordx4 v246, v[190:193], s[100:101]
	v_mul_f32_e32 v247, v46, v46
	v_fmac_f32_e32 v247, v47, v47
	v_fmac_f32_e32 v247, v48, v48
	v_fmac_f32_e32 v247, v49, v49
	v_mul_f32_e32 v254, v42, v42
	v_fmac_f32_e32 v254, v43, v43
	v_fmac_f32_e32 v254, v44, v44
	v_fmac_f32_e32 v254, v45, v45
	v_max3_f32 v252, |v46|, |v47|, |v48|
	v_max3_f32 v252, |v49|, |v42|, v252
	v_max3_f32 v252, |v43|, |v44|, v252
	v_max_f32_e64 v252, |v45|, v252
	s_waitcnt vmcnt(15)
	v_lshlrev_b32_e32 v248, 16, v194
	v_and_b32_e32 v249, 0xffff0000, v194
	v_lshlrev_b32_e32 v250, 16, v195
	v_and_b32_e32 v251, 0xffff0000, v195
	v_pk_add_f32 v[38:39], v[38:39], v[248:249]
	v_pk_add_f32 v[40:41], v[40:41], v[250:251]
	v_lshlrev_b32_e32 v248, 16, v196
	v_and_b32_e32 v249, 0xffff0000, v196
	v_lshlrev_b32_e32 v250, 16, v197
	v_and_b32_e32 v251, 0xffff0000, v197
	v_pk_add_f32 v[34:35], v[34:35], v[248:249]
	v_pk_add_f32 v[36:37], v[36:37], v[250:251]
	v_cvt_pk_bf16_f32 v194, v38, v39
	v_cvt_pk_bf16_f32 v195, v40, v41
	v_cvt_pk_bf16_f32 v196, v34, v35
	v_cvt_pk_bf16_f32 v197, v36, v37
	v_add_u32_e32 v255, 0x124800, v245
	global_store_dwordx4 v255, v[194:197], s[100:101] offset:256
	v_fmac_f32_e32 v247, v38, v38
	v_fmac_f32_e32 v247, v39, v39
	v_fmac_f32_e32 v247, v40, v40
	v_fmac_f32_e32 v247, v41, v41
	v_fmac_f32_e32 v254, v34, v34
	v_fmac_f32_e32 v254, v35, v35
	v_fmac_f32_e32 v254, v36, v36
	v_fmac_f32_e32 v254, v37, v37
	v_max3_f32 v252, |v38|, |v39|, v252
	v_max_f32_e64 v252, |v40|, v252
	v_max3_f32 v252, |v41|, |v34|, v252
	v_max3_f32 v252, |v35|, |v36|, v252
	v_max_f32_e64 v252, |v37|, v252
	v_add_f32_e32 v46, v247, v254
	v_mov_b32_e32 v48, v252
	s_waitcnt vmcnt(15)
	v_lshlrev_b32_e32 v248, 16, v198
	v_and_b32_e32 v249, 0xffff0000, v198
	v_lshlrev_b32_e32 v250, 16, v199
	v_and_b32_e32 v251, 0xffff0000, v199
	v_pk_add_f32 v[30:31], v[30:31], v[248:249]
	v_pk_add_f32 v[32:33], v[32:33], v[250:251]
	v_lshlrev_b32_e32 v248, 16, v200
	v_and_b32_e32 v249, 0xffff0000, v200
	v_lshlrev_b32_e32 v250, 16, v201
	v_and_b32_e32 v251, 0xffff0000, v201
	v_pk_add_f32 v[26:27], v[26:27], v[248:249]
	v_pk_add_f32 v[28:29], v[28:29], v[250:251]
	v_cvt_pk_bf16_f32 v198, v30, v31
	v_cvt_pk_bf16_f32 v199, v32, v33
	v_cvt_pk_bf16_f32 v200, v26, v27
	v_cvt_pk_bf16_f32 v201, v28, v29
	v_add_u32_e32 v246, 0x145000, v245
	global_store_dwordx4 v246, v[198:201], s[100:101]
	v_mul_f32_e32 v247, v30, v30
	v_fmac_f32_e32 v247, v31, v31
	v_fmac_f32_e32 v247, v32, v32
	v_fmac_f32_e32 v247, v33, v33
	v_mul_f32_e32 v254, v26, v26
	v_fmac_f32_e32 v254, v27, v27
	v_fmac_f32_e32 v254, v28, v28
	v_fmac_f32_e32 v254, v29, v29
	v_max3_f32 v252, |v30|, |v31|, |v32|
	v_max3_f32 v252, |v33|, |v26|, v252
	v_max3_f32 v252, |v27|, |v28|, v252
	v_max_f32_e64 v252, |v29|, v252
	s_waitcnt vmcnt(15)
	v_lshlrev_b32_e32 v248, 16, v202
	v_and_b32_e32 v249, 0xffff0000, v202
	v_lshlrev_b32_e32 v250, 16, v203
	v_and_b32_e32 v251, 0xffff0000, v203
	v_pk_add_f32 v[22:23], v[22:23], v[248:249]
	v_pk_add_f32 v[24:25], v[24:25], v[250:251]
	v_lshlrev_b32_e32 v248, 16, v204
	v_and_b32_e32 v249, 0xffff0000, v204
	v_lshlrev_b32_e32 v250, 16, v205
	v_and_b32_e32 v251, 0xffff0000, v205
	v_pk_add_f32 v[18:19], v[18:19], v[248:249]
	v_pk_add_f32 v[20:21], v[20:21], v[250:251]
	v_cvt_pk_bf16_f32 v202, v22, v23
	v_cvt_pk_bf16_f32 v203, v24, v25
	v_cvt_pk_bf16_f32 v204, v18, v19
	v_cvt_pk_bf16_f32 v205, v20, v21
	v_add_u32_e32 v255, 0x145000, v245
	global_store_dwordx4 v255, v[202:205], s[100:101] offset:256
	v_fmac_f32_e32 v247, v22, v22
	v_fmac_f32_e32 v247, v23, v23
	v_fmac_f32_e32 v247, v24, v24
	v_fmac_f32_e32 v247, v25, v25
	v_fmac_f32_e32 v254, v18, v18
	v_fmac_f32_e32 v254, v19, v19
	v_fmac_f32_e32 v254, v20, v20
	v_fmac_f32_e32 v254, v21, v21
	v_max3_f32 v252, |v22|, |v23|, v252
	v_max_f32_e64 v252, |v24|, v252
	v_max3_f32 v252, |v25|, |v18|, v252
	v_max3_f32 v252, |v19|, |v20|, v252
	v_max_f32_e64 v252, |v21|, v252
	v_add_f32_e32 v30, v247, v254
	v_mov_b32_e32 v32, v252
	s_waitcnt vmcnt(15)
;     __device__ __forceinline__ void operator()(EPI_ARGS) const {
;     ...
;                 ss += __shfl_xor(ss, 16); ss += __shfl_xor(ss, 32); ssv[ai * 4 + m] = ss;
;                 if (rowmax) { mx = fmaxf(mx, __shfl_xor(mx, 16)); mx = fmaxf(mx, __shfl_xor(mx, 32)); } mxv[ai * 4 + m] = mx; }
;             asm volatile("" ::: "memory"); }
;         float s0 = 0.f, s1 = 0.f, m0 = 0.f, m1 = 0.f;
; #pragma unroll
;         for (int k = 0; k < 8; ++k) if ((k >> 1) == fq) { if (k & 1) { s1 = ssv[k]; m1 = mxv[k]; } else { s0 = ssv[k]; m0 = mxv[k]; } }
;         const int rq = row0 + (fq >> 1) * HALF + (fq & 1) * 32;
;         __hip_atomic_fetch_add(rowsq + rq, s0, __ATOMIC_RELAXED, __HIP_MEMORY_SCOPE_AGENT); __hip_atomic_fetch_add(rowsq + rq + 16, s1, __ATOMIC_RELAXED, __HIP_MEMORY_SCOPE_AGENT);
;         if (rowmax) { __hip_atomic_fetch_max(rowmax + rq, __float_as_uint(m0), __ATOMIC_RELAXED, __HIP_MEMORY_SCOPE_AGENT); __hip_atomic_fetch_max(rowmax + rq + 16, __float_as_uint(m1), __ATOMIC_RELAXED, __HIP_MEMORY_SCOPE_AGENT); }
	v_lshlrev_b32_e32 v248, 16, v206
	v_and_b32_e32 v249, 0xffff0000, v206
	v_lshlrev_b32_e32 v250, 16, v207
	v_and_b32_e32 v251, 0xffff0000, v207
	v_pk_add_f32 v[14:15], v[14:15], v[248:249]
	v_pk_add_f32 v[16:17], v[16:17], v[250:251]
	v_lshlrev_b32_e32 v248, 16, v208
	v_and_b32_e32 v249, 0xffff0000, v208
	v_lshlrev_b32_e32 v250, 16, v209
	v_and_b32_e32 v251, 0xffff0000, v209
	v_pk_add_f32 v[10:11], v[10:11], v[248:249]
	v_pk_add_f32 v[12:13], v[12:13], v[250:251]
	v_cvt_pk_bf16_f32 v206, v14, v15
	v_cvt_pk_bf16_f32 v207, v16, v17
	v_cvt_pk_bf16_f32 v208, v10, v11
	v_cvt_pk_bf16_f32 v209, v12, v13
	v_add_u32_e32 v246, 0x165800, v245
	global_store_dwordx4 v246, v[206:209], s[100:101]
	v_mul_f32_e32 v247, v14, v14
	v_fmac_f32_e32 v247, v15, v15
	v_fmac_f32_e32 v247, v16, v16
	v_fmac_f32_e32 v247, v17, v17
	v_mul_f32_e32 v254, v10, v10
	v_fmac_f32_e32 v254, v11, v11
	v_fmac_f32_e32 v254, v12, v12
	v_fmac_f32_e32 v254, v13, v13
	v_max3_f32 v252, |v14|, |v15|, |v16|
	v_max3_f32 v252, |v17|, |v10|, v252
	v_max3_f32 v252, |v11|, |v12|, v252
	v_max_f32_e64 v252, |v13|, v252
	s_waitcnt vmcnt(15)
	v_lshlrev_b32_e32 v248, 16, v210
	v_and_b32_e32 v249, 0xffff0000, v210
	v_lshlrev_b32_e32 v250, 16, v211
	v_and_b32_e32 v251, 0xffff0000, v211
	v_pk_add_f32 v[6:7], v[6:7], v[248:249]
	v_pk_add_f32 v[8:9], v[8:9], v[250:251]
	v_lshlrev_b32_e32 v248, 16, v212
	v_and_b32_e32 v249, 0xffff0000, v212
	v_lshlrev_b32_e32 v250, 16, v213
	v_and_b32_e32 v251, 0xffff0000, v213
	v_pk_add_f32 v[2:3], v[2:3], v[248:249]
	v_pk_add_f32 v[4:5], v[4:5], v[250:251]
	v_cvt_pk_bf16_f32 v210, v6, v7
	v_cvt_pk_bf16_f32 v211, v8, v9
	v_cvt_pk_bf16_f32 v212, v2, v3
	v_cvt_pk_bf16_f32 v213, v4, v5
	v_add_u32_e32 v255, 0x165800, v245
	global_store_dwordx4 v255, v[210:213], s[100:101] offset:256
	v_fmac_f32_e32 v247, v6, v6
	v_fmac_f32_e32 v247, v7, v7
	v_fmac_f32_e32 v247, v8, v8
	v_fmac_f32_e32 v247, v9, v9
	v_fmac_f32_e32 v254, v2, v2
	v_fmac_f32_e32 v254, v3, v3
	v_fmac_f32_e32 v254, v4, v4
	v_fmac_f32_e32 v254, v5, v5
	v_max3_f32 v252, |v6|, |v7|, v252
	v_max_f32_e64 v252, |v8|, v252
	v_max3_f32 v252, |v9|, |v2|, v252
	v_max3_f32 v252, |v3|, |v4|, v252
	v_max_f32_e64 v252, |v5|, v252
	v_add_f32_e32 v14, v247, v254
	v_mov_b32_e32 v16, v252
	v_and_b32_e32 v255, 63, v0
	v_xor_b32_e32 v252, 16, v255
	v_xor_b32_e32 v253, 32, v255
	v_lshlrev_b32_e32 v252, 2, v252
	v_lshlrev_b32_e32 v253, 2, v253
	ds_bpermute_b32 v127, v252, v126
	ds_bpermute_b32 v129, v252, v128
	ds_bpermute_b32 v111, v252, v110
	ds_bpermute_b32 v113, v252, v112
	ds_bpermute_b32 v95, v252, v94
	ds_bpermute_b32 v97, v252, v96
	ds_bpermute_b32 v79, v252, v78
	ds_bpermute_b32 v81, v252, v80
	ds_bpermute_b32 v63, v252, v62
	ds_bpermute_b32 v65, v252, v64
	ds_bpermute_b32 v47, v252, v46
	ds_bpermute_b32 v49, v252, v48
	ds_bpermute_b32 v31, v252, v30
	ds_bpermute_b32 v33, v252, v32
	ds_bpermute_b32 v15, v252, v14
	ds_bpermute_b32 v17, v252, v16
	s_waitcnt lgkmcnt(0)
	v_add_f32_e32 v126, v126, v127
	v_max_f32_e32 v128, v128, v129
	v_add_f32_e32 v110, v110, v111
	v_max_f32_e32 v112, v112, v113
	v_add_f32_e32 v94, v94, v95
	v_max_f32_e32 v96, v96, v97
	v_add_f32_e32 v78, v78, v79
	v_max_f32_e32 v80, v80, v81
	v_add_f32_e32 v62, v62, v63
	v_max_f32_e32 v64, v64, v65
	v_add_f32_e32 v46, v46, v47
	v_max_f32_e32 v48, v48, v49
	v_add_f32_e32 v30, v30, v31
	v_max_f32_e32 v32, v32, v33
	v_add_f32_e32 v14, v14, v15
	v_max_f32_e32 v16, v16, v17
	ds_bpermute_b32 v127, v253, v126
	ds_bpermute_b32 v129, v253, v128
	ds_bpermute_b32 v111, v253, v110
	ds_bpermute_b32 v113, v253, v112
	ds_bpermute_b32 v95, v253, v94
	ds_bpermute_b32 v97, v253, v96
	ds_bpermute_b32 v79, v253, v78
	ds_bpermute_b32 v81, v253, v80
	ds_bpermute_b32 v63, v253, v62
	ds_bpermute_b32 v65, v253, v64
	ds_bpermute_b32 v47, v253, v46
	ds_bpermute_b32 v49, v253, v48
	ds_bpermute_b32 v31, v253, v30
	ds_bpermute_b32 v33, v253, v32
	ds_bpermute_b32 v15, v253, v14
	ds_bpermute_b32 v17, v253, v16
	s_waitcnt lgkmcnt(0)
	v_add_f32_e32 v126, v126, v127
	v_max_f32_e32 v128, v128, v129
	v_add_f32_e32 v110, v110, v111
	v_max_f32_e32 v112, v112, v113
	v_add_f32_e32 v94, v94, v95
	v_max_f32_e32 v96, v96, v97
	v_add_f32_e32 v78, v78, v79
	v_max_f32_e32 v80, v80, v81
	v_add_f32_e32 v62, v62, v63
	v_max_f32_e32 v64, v64, v65
	v_add_f32_e32 v46, v46, v47
	v_max_f32_e32 v48, v48, v49
	v_add_f32_e32 v30, v30, v31
	v_max_f32_e32 v32, v32, v33
	v_add_f32_e32 v14, v14, v15
	v_max_f32_e32 v16, v16, v17
	v_cndmask_b32_e64 v248, 0, v126, s[2:3]
	v_cndmask_b32_e64 v249, 0, v110, s[2:3]
	v_cndmask_b32_e64 v248, v248, v94, s[4:5]
	v_cndmask_b32_e64 v249, v249, v78, s[4:5]
	v_cndmask_b32_e64 v248, v248, v62, s[6:7]
	v_cndmask_b32_e64 v249, v249, v46, s[6:7]
	v_cndmask_b32_e64 v248, v248, v30, s[8:9]
	v_cndmask_b32_e64 v249, v249, v14, s[8:9]
	v_lshl_add_u32 v250, s72, 8, v181
	v_add_u32_e32 v250, v180, v250
	v_lshlrev_b32_e32 v250, 2, v250
	global_atomic_add_f32 v250, v248, s[54:55]
	global_atomic_add_f32 v250, v249, s[54:55] offset:64
	v_cndmask_b32_e64 v247, 0, v128, s[2:3]
	v_cndmask_b32_e64 v254, 0, v112, s[2:3]
	v_cndmask_b32_e64 v247, v247, v96, s[4:5]
	v_cndmask_b32_e64 v254, v254, v80, s[4:5]
	v_cndmask_b32_e64 v247, v247, v64, s[6:7]
	v_cndmask_b32_e64 v254, v254, v48, s[6:7]
	v_cndmask_b32_e64 v247, v247, v32, s[8:9]
	v_cndmask_b32_e64 v254, v254, v16, s[8:9]
	global_atomic_umax v250, v247, s[56:57]
	global_atomic_umax v250, v254, s[56:57] offset:64
	s_and_b64 vcc, exec, s[10:11]
	s_mov_b64 s[10:11], -1
	s_cbranch_vccnz .LBB0_992
	s_andn2_b64 vcc, exec, s[0:1]
	s_cbranch_vccnz .LBB0_991
	s_barrier
	s_branch .LBB0_991

; #define GAS __attribute__((address_space(1)))
; __device__ __forceinline__ float bf_lo(unsigned w) { return __uint_as_float(w << 16); }
; __device__ __forceinline__ float bf_hi(unsigned w) { return __uint_as_float(w & 0xffff0000u); }
; __device__ __forceinline__ unsigned pack4_i8(int a, int b, int c, int d) { return (unsigned)(a & 0xff) | ((unsigned)(b & 0xff) << 8) | ((unsigned)(c & 0xff) << 16) | ((unsigned)d << 24); }
; __device__ __forceinline__ int quant_i8(float x, float inv) { return (int)fminf(fmaxf(__builtin_rintf(x * inv), -127.0f), 127.0f); }
; __device__ __forceinline__ void quant_row_i8(const bf16* hrow, unsigned char* qrow, float amax, int lane) {
;     const float inv = amax > 0.f ? 127.0f / amax : 0.f;
; #pragma unroll
;     for (int it = 0; it < 4; ++it) { const GAS u32x4* src = (const GAS u32x4*)(hrow + it * 1024 + lane * 16); const u32x4 a = src[0], b = src[1];
;         u32x4 o;
;         o.x = pack4_i8(quant_i8(bf_lo(a.x), inv), quant_i8(bf_hi(a.x), inv), quant_i8(bf_lo(a.y), inv), quant_i8(bf_hi(a.y), inv));
;         o.y = pack4_i8(quant_i8(bf_lo(a.z), inv), quant_i8(bf_hi(a.z), inv), quant_i8(bf_lo(a.w), inv), quant_i8(bf_hi(a.w), inv));
;         o.z = pack4_i8(quant_i8(bf_lo(b.x), inv), quant_i8(bf_hi(b.x), inv), quant_i8(bf_lo(b.y), inv), quant_i8(bf_hi(b.y), inv));
;         o.w = pack4_i8(quant_i8(bf_lo(b.z), inv), quant_i8(bf_hi(b.z), inv), quant_i8(bf_lo(b.w), inv), quant_i8(bf_hi(b.w), inv));
;         *(GAS u32x4*)(qrow + it * 1024 + lane * 16) = o; }
; __global__ void __launch_bounds__(NWAVES * 64, 2) fwd_kernel(Args args) {
;     ...
;         for (int m = gw; m < MTOK; m += NGW) quant_row_i8(HB + (size_t)m * DM, A8 + (size_t)m * DM, __uint_as_float(__hip_atomic_load(rmaxU + m, __ATOMIC_RELAXED, __HIP_MEMORY_SCOPE_AGENT)), lane);
.LBB0_1120:
	s_or_b64 exec, exec, s[0:1]
	v_readlane_b32 s36, v244, 2
	s_cmpk_gt_i32 s18, 0x3fff
	v_readlane_b32 s50, v244, 16
	v_readlane_b32 s51, v244, 17
	s_waitcnt lgkmcnt(0)
	s_barrier
	v_readlane_b32 s37, v244, 3
	v_readlane_b32 s38, v244, 4
	v_readlane_b32 s39, v244, 5
	v_readlane_b32 s40, v244, 6
	v_readlane_b32 s41, v244, 7
	v_readlane_b32 s42, v244, 8
	v_readlane_b32 s43, v244, 9
	v_readlane_b32 s44, v244, 10
	v_readlane_b32 s45, v244, 11
	v_readlane_b32 s46, v244, 12
	v_readlane_b32 s47, v244, 13
	v_readlane_b32 s48, v244, 14
	v_readlane_b32 s49, v244, 15
	s_cbranch_scc1 .LBB0_1123
	s_ashr_i32 s19, s18, 31
	s_lshl_b64 s[0:1], s[18:19], 2
	s_add_u32 s14, s0, 0x85800
	v_and_b32_e32 v1, 0x3f0, v1
	s_addc_u32 s15, s1, 0
	s_lshl_b64 s[2:3], s[18:19], 12
	s_ashr_i32 s21, s20, 31
	s_waitcnt vmcnt(47)
	v_or_b32_e32 v2, s2, v1
	s_mul_i32 s4, s18, 0x2080
	s_mov_b32 s5, 0
	v_and_b32_e32 v1, 63, v0
	s_lshl_b64 s[0:1], s[20:21], 2
	v_mov_b32_e32 v3, s3
	s_lshl_b64 s[2:3], s[20:21], 12
	v_lshl_add_u32 v4, v1, 5, s4
	v_mov_b32_e32 v5, s5
	s_mul_i32 s4, s20, 0x2080
	s_mov_b32 s5, 0
	v_mov_b32_e32 v1, 0
	s_mov_b32 s17, 0x42fe0000
	s_mov_b64 s[6:7], 0
	s_mov_b32 s19, 0
	s_mov_b32 s21, 0xc2fe0000
	s_waitcnt vmcnt(45)
	v_mov_b32_e32 v12, 0x42fe0000
	s_mov_b32 s23, 0x40c0c00
	s_mov_b32 s24, 0x1c700000
	s_mov_b64 s[8:9], 0x800
	s_mov_b64 s[10:11], 0x1000
	s_mov_b32 s25, 0x1000
	s_mov_b64 s[12:13], 0x1800
	s_mov_b32 s26, s18
.LBB0_1122:
	v_lshl_add_u64 v[6:7], s[100:101], 0, v[4:5]
	s_waitcnt vmcnt(40)
	v_add_co_u32_e32 v22, vcc, s19, v6
	s_add_u32 s40, s50, s14
	s_nop 0
	v_addc_co_u32_e32 v23, vcc, 0, v7, vcc
	s_addc_u32 s41, s51, s15
	v_lshl_add_u64 v[18:19], v[6:7], 0, s[6:7]
	v_add_co_u32_e32 v10, vcc, s25, v6
	v_lshl_add_u64 v[8:9], s[50:51], 0, v[2:3]
	s_nop 0
	v_addc_co_u32_e32 v11, vcc, 0, v7, vcc
	global_load_dword v13, v1, s[40:41] sc1
	global_load_dwordx4 v[14:17], v[10:11], off offset:-4096
	s_nop 0
	global_load_dwordx4 v[18:21], v[18:19], off offset:16
	v_add_co_u32_e32 v8, vcc, s24, v8
	v_lshl_add_u64 v[24:25], v[6:7], 0, s[8:9]
	s_nop 0
	v_addc_co_u32_e32 v9, vcc, 0, v9, vcc
	s_waitcnt vmcnt(42)
	v_lshl_add_u64 v[26:27], v[6:7], 0, s[10:11]
	v_lshl_add_u64 v[6:7], v[6:7], 0, s[12:13]
	s_add_i32 s26, s26, s20
	s_add_u32 s14, s14, s0
	s_addc_u32 s15, s15, s1
	v_lshl_add_u64 v[2:3], v[2:3], 0, s[2:3]
	v_lshl_add_u64 v[4:5], v[4:5], 0, s[4:5]
	s_cmpk_gt_i32 s26, 0x3fff
	s_waitcnt vmcnt(2)
	v_div_scale_f32 v28, s[28:29], v13, v13, s17
	v_rcp_f32_e32 v38, v28
	v_div_scale_f32 v29, vcc, s17, v13, s17
	s_waitcnt vmcnt(1)
	v_lshlrev_b32_e32 v30, 16, v14
	v_fma_f32 v39, -v28, v38, 1.0
	v_fmac_f32_e32 v38, v39, v38
	v_mul_f32_e32 v39, v29, v38
	v_fma_f32 v40, -v28, v39, v29
	v_fmac_f32_e32 v39, v40, v38
	v_fma_f32 v28, -v28, v39, v29
	v_div_fmas_f32 v28, v28, v38, v39
	v_div_fixup_f32 v28, v28, v13, s17
	v_cmp_lt_f32_e32 vcc, 0, v13
	v_and_b32_e32 v14, 0xffff0000, v14
	v_lshlrev_b32_e32 v32, 16, v16
	v_and_b32_e32 v16, 0xffff0000, v16
	s_waitcnt vmcnt(0)
	v_lshlrev_b32_e32 v34, 16, v18
	v_and_b32_e32 v18, 0xffff0000, v18
	v_lshlrev_b32_e32 v36, 16, v20
	v_and_b32_e32 v20, 0xffff0000, v20
	v_cndmask_b32_e32 v13, 0, v28, vcc
	v_lshlrev_b32_e32 v31, 16, v15
	v_and_b32_e32 v15, 0xffff0000, v15
	v_lshlrev_b32_e32 v33, 16, v17
	v_and_b32_e32 v17, 0xffff0000, v17
	v_lshlrev_b32_e32 v35, 16, v19
	v_and_b32_e32 v19, 0xffff0000, v19
	v_lshlrev_b32_e32 v37, 16, v21
	v_and_b32_e32 v21, 0xffff0000, v21
	v_mul_f32_e32 v14, v13, v14
	v_mul_f32_e32 v16, v13, v16
	v_mul_f32_e32 v18, v13, v18
	v_mul_f32_e32 v20, v13, v20
	v_mul_f32_e32 v28, v13, v30
	v_mul_f32_e32 v29, v13, v31
	v_mul_f32_e32 v15, v13, v15
	v_mul_f32_e32 v30, v13, v32
	v_mul_f32_e32 v31, v13, v33
	v_mul_f32_e32 v17, v13, v17
	v_mul_f32_e32 v32, v13, v34
	v_mul_f32_e32 v33, v13, v35
	v_mul_f32_e32 v19, v13, v19
	v_mul_f32_e32 v34, v13, v36
	v_mul_f32_e32 v35, v13, v37
	v_mul_f32_e32 v21, v13, v21
	v_rndne_f32_e32 v14, v14
	v_rndne_f32_e32 v16, v16
	v_rndne_f32_e32 v18, v18
	v_rndne_f32_e32 v20, v20
	v_rndne_f32_e32 v28, v28
	v_rndne_f32_e32 v29, v29
	v_rndne_f32_e32 v15, v15
	v_rndne_f32_e32 v30, v30
	v_rndne_f32_e32 v31, v31
	v_rndne_f32_e32 v17, v17
	v_rndne_f32_e32 v32, v32
	v_rndne_f32_e32 v33, v33
	v_rndne_f32_e32 v19, v19
	v_rndne_f32_e32 v34, v34
	v_rndne_f32_e32 v35, v35
	v_rndne_f32_e32 v21, v21
	v_med3_f32 v14, v14, s21, v12
	v_med3_f32 v16, v16, s21, v12
	v_med3_f32 v18, v18, s21, v12
	v_med3_f32 v20, v20, s21, v12
	v_med3_f32 v28, v28, s21, v12
	v_med3_f32 v29, v29, s21, v12
	v_med3_f32 v15, v15, s21, v12
	v_med3_f32 v30, v30, s21, v12
	v_med3_f32 v31, v31, s21, v12
	v_med3_f32 v17, v17, s21, v12
	v_med3_f32 v32, v32, s21, v12
	v_med3_f32 v33, v33, s21, v12
	v_med3_f32 v19, v19, s21, v12
	v_med3_f32 v34, v34, s21, v12
	v_med3_f32 v35, v35, s21, v12
	v_med3_f32 v21, v21, s21, v12
	v_cvt_i32_f32_e32 v14, v14
	v_cvt_i32_f32_e32 v16, v16
	v_cvt_i32_f32_e32 v18, v18
	v_cvt_i32_f32_e32 v20, v20
	v_cvt_i32_f32_e32 v28, v28
	v_cvt_i32_f32_sdwa v29, v29 dst_sel:WORD_1 dst_unused:UNUSED_PAD src0_sel:DWORD
	v_cvt_i32_f32_e32 v15, v15
	v_cvt_i32_f32_e32 v30, v30
	v_cvt_i32_f32_sdwa v31, v31 dst_sel:WORD_1 dst_unused:UNUSED_PAD src0_sel:DWORD
	v_cvt_i32_f32_e32 v17, v17
	v_cvt_i32_f32_e32 v32, v32
	v_cvt_i32_f32_sdwa v33, v33 dst_sel:WORD_1 dst_unused:UNUSED_PAD src0_sel:DWORD
	v_cvt_i32_f32_e32 v19, v19
	v_cvt_i32_f32_e32 v34, v34
	v_cvt_i32_f32_sdwa v35, v35 dst_sel:WORD_1 dst_unused:UNUSED_PAD src0_sel:DWORD
	v_cvt_i32_f32_e32 v21, v21
	v_lshlrev_b32_e32 v14, 8, v14
	v_lshlrev_b32_e32 v16, 8, v16
	v_lshlrev_b32_e32 v18, 8, v18
	v_lshlrev_b32_e32 v20, 8, v20
	v_and_b32_e32 v29, 0xff0000, v29
	v_perm_b32 v15, v15, v28, s23
	v_and_b32_e32 v28, 0xff0000, v31
	v_perm_b32 v17, v17, v30, s23
	v_and_b32_e32 v30, 0xff0000, v33
	v_perm_b32 v19, v19, v32, s23
	v_and_b32_e32 v31, 0xff0000, v35
	v_perm_b32 v21, v21, v34, s23
	v_and_b32_e32 v14, 0xff00, v14
	v_and_b32_e32 v16, 0xff00, v16
	v_and_b32_e32 v18, 0xff00, v18
	v_and_b32_e32 v20, 0xff00, v20
	v_or3_b32 v14, v15, v14, v29
	v_or3_b32 v15, v17, v16, v28
	v_or3_b32 v16, v19, v18, v30
	v_or3_b32 v17, v21, v20, v31
	global_store_dwordx4 v[8:9], v[14:17], off
	global_load_dwordx4 v[14:17], v[22:23], off offset:2048
	s_nop 0
	global_load_dwordx4 v[18:21], v[24:25], off offset:16
	s_waitcnt vmcnt(1)
; #define GAS __attribute__((address_space(1)))
; __device__ __forceinline__ float bf_lo(unsigned w) { return __uint_as_float(w << 16); }
; __device__ __forceinline__ float bf_hi(unsigned w) { return __uint_as_float(w & 0xffff0000u); }
; __device__ __forceinline__ unsigned pack4_i8(int a, int b, int c, int d) { return (unsigned)(a & 0xff) | ((unsigned)(b & 0xff) << 8) | ((unsigned)(c & 0xff) << 16) | ((unsigned)d << 24); }
; __device__ __forceinline__ int quant_i8(float x, float inv) { return (int)fminf(fmaxf(__builtin_rintf(x * inv), -127.0f), 127.0f); }
; __device__ __forceinline__ void quant_row_i8(const bf16* hrow, unsigned char* qrow, float amax, int lane) {
;     ...
;     for (int it = 0; it < 4; ++it) { const GAS u32x4* src = (const GAS u32x4*)(hrow + it * 1024 + lane * 16); const u32x4 a = src[0], b = src[1];
;         u32x4 o;
;         o.x = pack4_i8(quant_i8(bf_lo(a.x), inv), quant_i8(bf_hi(a.x), inv), quant_i8(bf_lo(a.y), inv), quant_i8(bf_hi(a.y), inv));
;         o.y = pack4_i8(quant_i8(bf_lo(a.z), inv), quant_i8(bf_hi(a.z), inv), quant_i8(bf_lo(a.w), inv), quant_i8(bf_hi(a.w), inv));
;         o.z = pack4_i8(quant_i8(bf_lo(b.x), inv), quant_i8(bf_hi(b.x), inv), quant_i8(bf_lo(b.y), inv), quant_i8(bf_hi(b.y), inv));
;         o.w = pack4_i8(quant_i8(bf_lo(b.z), inv), quant_i8(bf_hi(b.z), inv), quant_i8(bf_lo(b.w), inv), quant_i8(bf_hi(b.w), inv));
;         *(GAS u32x4*)(qrow + it * 1024 + lane * 16) = o; }
	v_lshlrev_b32_e32 v22, 16, v14
	v_and_b32_e32 v14, 0xffff0000, v14
	v_lshlrev_b32_e32 v24, 16, v16
	v_and_b32_e32 v16, 0xffff0000, v16
	s_waitcnt vmcnt(0)
	v_lshlrev_b32_e32 v28, 16, v18
	v_and_b32_e32 v18, 0xffff0000, v18
	v_lshlrev_b32_e32 v30, 16, v20
	v_and_b32_e32 v20, 0xffff0000, v20
	v_lshlrev_b32_e32 v23, 16, v15
	v_and_b32_e32 v15, 0xffff0000, v15
	v_lshlrev_b32_e32 v25, 16, v17
	v_and_b32_e32 v17, 0xffff0000, v17
	v_lshlrev_b32_e32 v29, 16, v19
	v_and_b32_e32 v19, 0xffff0000, v19
	v_lshlrev_b32_e32 v31, 16, v21
	v_and_b32_e32 v21, 0xffff0000, v21
	v_mul_f32_e32 v14, v13, v14
	v_mul_f32_e32 v16, v13, v16
	v_mul_f32_e32 v18, v13, v18
	v_mul_f32_e32 v20, v13, v20
	v_mul_f32_e32 v22, v13, v22
	v_mul_f32_e32 v23, v13, v23
	v_mul_f32_e32 v15, v13, v15
	v_mul_f32_e32 v24, v13, v24
	v_mul_f32_e32 v25, v13, v25
	v_mul_f32_e32 v17, v13, v17
	v_mul_f32_e32 v28, v13, v28
	v_mul_f32_e32 v29, v13, v29
	v_mul_f32_e32 v19, v13, v19
	v_mul_f32_e32 v30, v13, v30
	v_mul_f32_e32 v31, v13, v31
	v_mul_f32_e32 v21, v13, v21
	v_rndne_f32_e32 v14, v14
	v_rndne_f32_e32 v16, v16
	v_rndne_f32_e32 v18, v18
	v_rndne_f32_e32 v20, v20
	v_rndne_f32_e32 v22, v22
	v_rndne_f32_e32 v23, v23
	v_rndne_f32_e32 v15, v15
	v_rndne_f32_e32 v24, v24
	v_rndne_f32_e32 v25, v25
	v_rndne_f32_e32 v17, v17
	v_rndne_f32_e32 v28, v28
	v_rndne_f32_e32 v29, v29
	v_rndne_f32_e32 v19, v19
	v_rndne_f32_e32 v30, v30
	v_rndne_f32_e32 v31, v31
	v_rndne_f32_e32 v21, v21
	v_med3_f32 v14, v14, s21, v12
	v_med3_f32 v16, v16, s21, v12
	v_med3_f32 v18, v18, s21, v12
	v_med3_f32 v20, v20, s21, v12
	v_med3_f32 v22, v22, s21, v12
	v_med3_f32 v23, v23, s21, v12
	v_med3_f32 v15, v15, s21, v12
	v_med3_f32 v24, v24, s21, v12
	v_med3_f32 v25, v25, s21, v12
	v_med3_f32 v17, v17, s21, v12
	v_med3_f32 v28, v28, s21, v12
	v_med3_f32 v29, v29, s21, v12
	v_med3_f32 v19, v19, s21, v12
	v_med3_f32 v30, v30, s21, v12
	v_med3_f32 v31, v31, s21, v12
	v_med3_f32 v21, v21, s21, v12
	v_cvt_i32_f32_e32 v14, v14
	v_cvt_i32_f32_e32 v16, v16
	v_cvt_i32_f32_e32 v18, v18
	v_cvt_i32_f32_e32 v20, v20
	v_cvt_i32_f32_e32 v22, v22
	v_cvt_i32_f32_sdwa v23, v23 dst_sel:WORD_1 dst_unused:UNUSED_PAD src0_sel:DWORD
	v_cvt_i32_f32_e32 v15, v15
	v_cvt_i32_f32_e32 v24, v24
	v_cvt_i32_f32_sdwa v25, v25 dst_sel:WORD_1 dst_unused:UNUSED_PAD src0_sel:DWORD
	v_cvt_i32_f32_e32 v17, v17
	v_cvt_i32_f32_e32 v28, v28
	v_cvt_i32_f32_sdwa v29, v29 dst_sel:WORD_1 dst_unused:UNUSED_PAD src0_sel:DWORD
	v_cvt_i32_f32_e32 v19, v19
	v_cvt_i32_f32_e32 v30, v30
	v_cvt_i32_f32_sdwa v31, v31 dst_sel:WORD_1 dst_unused:UNUSED_PAD src0_sel:DWORD
	v_cvt_i32_f32_e32 v21, v21
	v_lshlrev_b32_e32 v14, 8, v14
	v_lshlrev_b32_e32 v16, 8, v16
	v_lshlrev_b32_e32 v18, 8, v18
	v_lshlrev_b32_e32 v20, 8, v20
	v_and_b32_e32 v23, 0xff0000, v23
	v_perm_b32 v15, v15, v22, s23
	v_and_b32_e32 v22, 0xff0000, v25
	v_perm_b32 v17, v17, v24, s23
	v_and_b32_e32 v24, 0xff0000, v29
	v_perm_b32 v19, v19, v28, s23
	v_and_b32_e32 v25, 0xff0000, v31
	v_perm_b32 v21, v21, v30, s23
	v_and_b32_e32 v14, 0xff00, v14
	v_and_b32_e32 v16, 0xff00, v16
	v_and_b32_e32 v18, 0xff00, v18
	v_and_b32_e32 v20, 0xff00, v20
	v_or3_b32 v14, v15, v14, v23
	v_or3_b32 v15, v17, v16, v22
	v_or3_b32 v16, v19, v18, v24
	v_or3_b32 v17, v21, v20, v25
	global_store_dwordx4 v[8:9], v[14:17], off offset:1024
	global_load_dwordx4 v[14:17], v[10:11], off
	s_nop 0
	global_load_dwordx4 v[18:21], v[26:27], off offset:16
	s_waitcnt vmcnt(1)
	v_lshlrev_b32_e32 v22, 16, v14
	v_and_b32_e32 v14, 0xffff0000, v14
	v_lshlrev_b32_e32 v24, 16, v16
	v_and_b32_e32 v16, 0xffff0000, v16
	s_waitcnt vmcnt(0)
; #define GAS __attribute__((address_space(1)))
; __device__ __forceinline__ float bf_lo(unsigned w) { return __uint_as_float(w << 16); }
; __device__ __forceinline__ float bf_hi(unsigned w) { return __uint_as_float(w & 0xffff0000u); }
; __device__ __forceinline__ unsigned pack4_i8(int a, int b, int c, int d) { return (unsigned)(a & 0xff) | ((unsigned)(b & 0xff) << 8) | ((unsigned)(c & 0xff) << 16) | ((unsigned)d << 24); }
; __device__ __forceinline__ int quant_i8(float x, float inv) { return (int)fminf(fmaxf(__builtin_rintf(x * inv), -127.0f), 127.0f); }
; __device__ __forceinline__ void quant_row_i8(const bf16* hrow, unsigned char* qrow, float amax, int lane) {
;     ...
;     for (int it = 0; it < 4; ++it) { const GAS u32x4* src = (const GAS u32x4*)(hrow + it * 1024 + lane * 16); const u32x4 a = src[0], b = src[1];
;         u32x4 o;
;         o.x = pack4_i8(quant_i8(bf_lo(a.x), inv), quant_i8(bf_hi(a.x), inv), quant_i8(bf_lo(a.y), inv), quant_i8(bf_hi(a.y), inv));
;         o.y = pack4_i8(quant_i8(bf_lo(a.z), inv), quant_i8(bf_hi(a.z), inv), quant_i8(bf_lo(a.w), inv), quant_i8(bf_hi(a.w), inv));
;         o.z = pack4_i8(quant_i8(bf_lo(b.x), inv), quant_i8(bf_hi(b.x), inv), quant_i8(bf_lo(b.y), inv), quant_i8(bf_hi(b.y), inv));
;         o.w = pack4_i8(quant_i8(bf_lo(b.z), inv), quant_i8(bf_hi(b.z), inv), quant_i8(bf_lo(b.w), inv), quant_i8(bf_hi(b.w), inv));
;         *(GAS u32x4*)(qrow + it * 1024 + lane * 16) = o; }
	v_lshlrev_b32_e32 v26, 16, v18
	v_and_b32_e32 v18, 0xffff0000, v18
	v_lshlrev_b32_e32 v28, 16, v20
	v_and_b32_e32 v20, 0xffff0000, v20
	v_lshlrev_b32_e32 v23, 16, v15
	v_and_b32_e32 v15, 0xffff0000, v15
	v_lshlrev_b32_e32 v25, 16, v17
	v_and_b32_e32 v17, 0xffff0000, v17
	v_lshlrev_b32_e32 v27, 16, v19
	v_and_b32_e32 v19, 0xffff0000, v19
	v_lshlrev_b32_e32 v29, 16, v21
	v_and_b32_e32 v21, 0xffff0000, v21
	v_mul_f32_e32 v14, v13, v14
	v_mul_f32_e32 v16, v13, v16
	v_mul_f32_e32 v18, v13, v18
	v_mul_f32_e32 v20, v13, v20
	v_mul_f32_e32 v22, v13, v22
	v_mul_f32_e32 v23, v13, v23
	v_mul_f32_e32 v15, v13, v15
	v_mul_f32_e32 v24, v13, v24
	v_mul_f32_e32 v25, v13, v25
	v_mul_f32_e32 v17, v13, v17
	v_mul_f32_e32 v26, v13, v26
	v_mul_f32_e32 v27, v13, v27
	v_mul_f32_e32 v19, v13, v19
	v_mul_f32_e32 v28, v13, v28
	v_mul_f32_e32 v29, v13, v29
	v_mul_f32_e32 v21, v13, v21
	v_rndne_f32_e32 v14, v14
	v_rndne_f32_e32 v16, v16
	v_rndne_f32_e32 v18, v18
	v_rndne_f32_e32 v20, v20
	v_rndne_f32_e32 v22, v22
	v_rndne_f32_e32 v23, v23
	v_rndne_f32_e32 v15, v15
	v_rndne_f32_e32 v24, v24
	v_rndne_f32_e32 v25, v25
	v_rndne_f32_e32 v17, v17
	v_rndne_f32_e32 v26, v26
	v_rndne_f32_e32 v27, v27
	v_rndne_f32_e32 v19, v19
	v_rndne_f32_e32 v28, v28
	v_rndne_f32_e32 v29, v29
	v_rndne_f32_e32 v21, v21
	v_med3_f32 v14, v14, s21, v12
	v_med3_f32 v16, v16, s21, v12
	v_med3_f32 v18, v18, s21, v12
	v_med3_f32 v20, v20, s21, v12
	v_med3_f32 v22, v22, s21, v12
	v_med3_f32 v23, v23, s21, v12
	v_med3_f32 v15, v15, s21, v12
	v_med3_f32 v24, v24, s21, v12
	v_med3_f32 v25, v25, s21, v12
	v_med3_f32 v17, v17, s21, v12
	v_med3_f32 v26, v26, s21, v12
	v_med3_f32 v27, v27, s21, v12
	v_med3_f32 v19, v19, s21, v12
	v_med3_f32 v28, v28, s21, v12
	v_med3_f32 v29, v29, s21, v12
	v_med3_f32 v21, v21, s21, v12
	v_cvt_i32_f32_e32 v14, v14
	v_cvt_i32_f32_e32 v16, v16
	v_cvt_i32_f32_e32 v18, v18
	v_cvt_i32_f32_e32 v20, v20
	v_cvt_i32_f32_e32 v22, v22
	v_cvt_i32_f32_sdwa v23, v23 dst_sel:WORD_1 dst_unused:UNUSED_PAD src0_sel:DWORD
	v_cvt_i32_f32_e32 v15, v15
	v_cvt_i32_f32_e32 v24, v24
	v_cvt_i32_f32_sdwa v25, v25 dst_sel:WORD_1 dst_unused:UNUSED_PAD src0_sel:DWORD
	v_cvt_i32_f32_e32 v17, v17
	v_cvt_i32_f32_e32 v26, v26
	v_cvt_i32_f32_sdwa v27, v27 dst_sel:WORD_1 dst_unused:UNUSED_PAD src0_sel:DWORD
	v_cvt_i32_f32_e32 v19, v19
	v_cvt_i32_f32_e32 v28, v28
	v_cvt_i32_f32_sdwa v29, v29 dst_sel:WORD_1 dst_unused:UNUSED_PAD src0_sel:DWORD
	v_cvt_i32_f32_e32 v21, v21
	v_lshlrev_b32_e32 v14, 8, v14
	v_lshlrev_b32_e32 v16, 8, v16
	v_lshlrev_b32_e32 v18, 8, v18
	v_lshlrev_b32_e32 v20, 8, v20
	v_and_b32_e32 v23, 0xff0000, v23
	v_perm_b32 v15, v15, v22, s23
	v_and_b32_e32 v22, 0xff0000, v25
	v_perm_b32 v17, v17, v24, s23
	v_and_b32_e32 v24, 0xff0000, v27
	v_perm_b32 v19, v19, v26, s23
	v_and_b32_e32 v25, 0xff0000, v29
	v_perm_b32 v21, v21, v28, s23
	v_and_b32_e32 v14, 0xff00, v14
	v_and_b32_e32 v16, 0xff00, v16
	v_and_b32_e32 v18, 0xff00, v18
	v_and_b32_e32 v20, 0xff00, v20
	v_or3_b32 v14, v15, v14, v23
	v_or3_b32 v15, v17, v16, v22
	v_or3_b32 v16, v19, v18, v24
	v_or3_b32 v17, v21, v20, v25
	global_store_dwordx4 v[8:9], v[14:17], off offset:2048
	global_load_dwordx4 v[14:17], v[10:11], off offset:2048
	s_nop 0
	global_load_dwordx4 v[18:21], v[6:7], off offset:16
	s_waitcnt vmcnt(1)
	v_lshlrev_b32_e32 v6, 16, v14
	v_and_b32_e32 v7, 0xffff0000, v14
	v_lshlrev_b32_e32 v10, 16, v15
	v_and_b32_e32 v11, 0xffff0000, v15
	v_lshlrev_b32_e32 v14, 16, v16
	v_and_b32_e32 v15, 0xffff0000, v16
	v_lshlrev_b32_e32 v16, 16, v17
	v_and_b32_e32 v17, 0xffff0000, v17
	s_waitcnt vmcnt(0)
	v_lshlrev_b32_e32 v22, 16, v18
	v_and_b32_e32 v18, 0xffff0000, v18
	v_lshlrev_b32_e32 v23, 16, v19
	v_and_b32_e32 v19, 0xffff0000, v19
	v_lshlrev_b32_e32 v24, 16, v20
	v_and_b32_e32 v20, 0xffff0000, v20
	v_lshlrev_b32_e32 v25, 16, v21
	v_and_b32_e32 v21, 0xffff0000, v21
	v_mul_f32_e32 v6, v13, v6
	v_mul_f32_e32 v7, v13, v7
	v_mul_f32_e32 v11, v13, v11
	v_mul_f32_e32 v14, v13, v14
	v_mul_f32_e32 v15, v13, v15
	v_mul_f32_e32 v16, v13, v16
	v_mul_f32_e32 v17, v13, v17
	v_mul_f32_e32 v22, v13, v22
	v_mul_f32_e32 v18, v13, v18
	v_mul_f32_e32 v19, v13, v19
	v_mul_f32_e32 v20, v13, v20
	v_mul_f32_e32 v10, v13, v10
	v_mul_f32_e32 v23, v13, v23
	v_mul_f32_e32 v24, v13, v24
	v_mul_f32_e32 v25, v13, v25
	v_mul_f32_e32 v13, v13, v21
	v_rndne_f32_e32 v6, v6
	v_rndne_f32_e32 v7, v7
	v_rndne_f32_e32 v11, v11
	v_rndne_f32_e32 v14, v14
	v_rndne_f32_e32 v15, v15
	v_rndne_f32_e32 v16, v16
	v_rndne_f32_e32 v17, v17
	v_rndne_f32_e32 v21, v22
	v_rndne_f32_e32 v18, v18
	v_rndne_f32_e32 v19, v19
	v_rndne_f32_e32 v20, v20
	v_rndne_f32_e32 v10, v10
	v_rndne_f32_e32 v22, v23
	v_rndne_f32_e32 v23, v24
	v_rndne_f32_e32 v24, v25
	v_rndne_f32_e32 v13, v13
	v_med3_f32 v6, v6, s21, v12
	v_med3_f32 v7, v7, s21, v12
	v_med3_f32 v11, v11, s21, v12
	v_med3_f32 v14, v14, s21, v12
	v_med3_f32 v15, v15, s21, v12
	v_med3_f32 v16, v16, s21, v12
	v_med3_f32 v17, v17, s21, v12
	v_med3_f32 v21, v21, s21, v12
	v_med3_f32 v18, v18, s21, v12
	v_med3_f32 v19, v19, s21, v12
	v_med3_f32 v20, v20, s21, v12
	v_med3_f32 v10, v10, s21, v12
	v_med3_f32 v22, v22, s21, v12
	v_med3_f32 v23, v23, s21, v12
	v_med3_f32 v24, v24, s21, v12
	v_med3_f32 v13, v13, s21, v12
	v_cvt_i32_f32_e32 v6, v6
	v_cvt_i32_f32_e32 v7, v7
	v_cvt_i32_f32_e32 v11, v11
	v_cvt_i32_f32_e32 v14, v14
	v_cvt_i32_f32_e32 v15, v15
	v_cvt_i32_f32_sdwa v16, v16 dst_sel:WORD_1 dst_unused:UNUSED_PAD src0_sel:DWORD
	v_cvt_i32_f32_e32 v17, v17
	v_cvt_i32_f32_e32 v21, v21
	v_cvt_i32_f32_e32 v18, v18
	v_cvt_i32_f32_e32 v19, v19
	v_cvt_i32_f32_e32 v20, v20
	v_cvt_i32_f32_sdwa v10, v10 dst_sel:WORD_1 dst_unused:UNUSED_PAD src0_sel:DWORD
	v_cvt_i32_f32_sdwa v22, v22 dst_sel:WORD_1 dst_unused:UNUSED_PAD src0_sel:DWORD
	v_cvt_i32_f32_e32 v23, v23
	v_cvt_i32_f32_sdwa v24, v24 dst_sel:WORD_1 dst_unused:UNUSED_PAD src0_sel:DWORD
	v_cvt_i32_f32_e32 v13, v13
	v_lshlrev_b32_e32 v7, 8, v7
	v_perm_b32 v6, v11, v6, s23
	v_lshlrev_b32_e32 v11, 8, v15
	v_and_b32_e32 v15, 0xff0000, v16
	v_perm_b32 v16, v17, v14, s23
	v_lshlrev_b32_e32 v14, 8, v18
	v_perm_b32 v18, v19, v21, s23
	v_lshlrev_b32_e32 v19, 8, v20
	v_and_b32_e32 v10, 0xff0000, v10
	v_and_b32_e32 v17, 0xff0000, v22
	v_and_b32_e32 v20, 0xff0000, v24
	v_perm_b32 v13, v13, v23, s23
	v_and_b32_e32 v7, 0xff00, v7
	v_and_b32_e32 v11, 0xff00, v11
	v_and_b32_e32 v21, 0xff00, v14
	v_and_b32_e32 v19, 0xff00, v19
	v_or3_b32 v14, v6, v7, v10
	v_or3_b32 v15, v16, v11, v15
	v_or3_b32 v16, v18, v21, v17
	v_or3_b32 v17, v13, v19, v20
	global_store_dwordx4 v[8:9], v[14:17], off offset:3072
	s_cbranch_scc0 .LBB0_1122

;     __device__ bool next(int i, Unit& u) const {
;         const long L = (long)i * G + c; if (L >= nwg) return false;
;         int wgid = (int)L; { const int q = nwg / NXCD, r = nwg % NXCD, xcd = wgid % NXCD, off = wgid / NXCD; wgid = (xcd < r ? xcd * (q + 1) : r * (q + 1) + (xcd - r) * q) + off; }
;         const int nig = wgm * nN, gid = wgid / nig, fm = gid * wgm, gsz = (nM - fm) < wgm ? (nM - fm) : wgm;
;         u.pm = fm + ((wgid % nig) % gsz); u.pn = (wgid % nig) / gsz; u.z = 0; return true;
; __global__ void __launch_bounds__(NWAVES * 64, 2) fwd_kernel(Args args) {
;     ...
;     if (IN(8)) {
;         pg8::Gemm g{FB, WDN, FF, FF, FF, 1, 1 << 30, 0, 0, 0, 0, 0}; pg8::StaticOrder S; S.init(MTOK / 256, DM / 256, G, bx, 4);
;         { pg8::EpiResid<true> E{HB, HB, rsq3, nullptr, DM, nullptr}; pg8::gemm_phase(ring, scr, g, S, E); }
.LBB0_1339:
	v_readlane_b32 s0, v244, 2
	v_readlane_b32 s14, v244, 16
	v_readlane_b32 s15, v244, 17
	s_add_u32 s34, s14, 0x60000
	s_addc_u32 s35, s15, 0
	v_readlane_b32 s1, v244, 3
	s_cmp_lt_i32 s96, 9
	v_readlane_b32 s2, v244, 4
	v_readlane_b32 s3, v244, 5
	s_cselect_b64 s[0:1], -1, 0
	s_cmp_gt_i32 s97, 8
	s_cselect_b64 s[2:3], -1, 0
	s_and_b64 s[0:1], s[0:1], s[2:3]
	s_andn2_b64 vcc, exec, s[0:1]
	v_readlane_b32 s4, v244, 6
	v_readlane_b32 s5, v244, 7
	v_readlane_b32 s6, v244, 8
	v_readlane_b32 s7, v244, 9
	v_readlane_b32 s8, v244, 10
	v_readlane_b32 s9, v244, 11
	v_readlane_b32 s10, v244, 12
	v_readlane_b32 s11, v244, 13
	v_readlane_b32 s12, v244, 14
	v_readlane_b32 s13, v244, 15
	s_cbranch_vccnz .LBB0_1422
	s_add_u32 s98, s14, 0x3a600000
	s_addc_u32 s99, s15, 0
	v_readlane_b32 s100, v244, 14
	v_readlane_b32 s101, v244, 15
	v_readfirstlane_b32 s2, v0
	s_lshr_b32 s3, s2, 6
	s_cmpk_gt_i32 s16, 0x3ff
	s_cbranch_scc1 .LBB0_1368
	s_ashr_i32 s14, s16, 31
	s_lshr_b32 s0, s14, 29
	s_add_i32 s6, s16, s0
	s_and_b32 s0, s6, -8
	s_sub_i32 s4, s16, s0
	s_cmp_gt_i32 s4, -1
	s_cbranch_scc0 .LBB0_1343
	s_lshl_b32 s5, s4, 7
	s_ashr_i32 s0, s6, 3
	s_cbranch_execz .LBB0_1344
	s_branch .LBB0_1345

; __device__ __forceinline__ unsigned cvt_pk_bf16(float lo, float hi) { unsigned r; asm volatile("v_cvt_pk_bf16_f32 %0, %1, %2" : "=v"(r) : "v"(lo), "v"(hi)); return r; }
; __device__ __forceinline__ float bf_lo(unsigned w) { return __uint_as_float(w << 16); }
; __device__ __forceinline__ float bf_hi(unsigned w) { return __uint_as_float(w & 0xffff0000u); }
;     __device__ __forceinline__ void operator()(EPI_ARGS) const {
;     ...
;                 for (int bj = 0; bj < 2; ++bj) { const size_t off = (size_t)(row0 + ai * HALF + m * 16) * ldc + col0 + bj * HALF;
;                     if (RES_BF16) { const u32x4 rw = *(const u32x4*)((const bf16*)resid + off); r0[m][bj] = __builtin_bit_cast(f32x4, rw); }
;                     else { r0[m][bj] = *(const f32x4*)((const float*)resid + off); r1[m][bj] = *(const f32x4*)((const float*)resid + off + 4); } }
; #pragma unroll
;             for (int m = 0; m < 4; ++m) { const int row = row0 + ai * HALF + m * 16; const size_t off = (size_t)row * ldc + col0; float ss = 0.f, mx = 0.f;
; #pragma unroll
;                 for (int bj = 0; bj < 2; ++bj) {
;                     f32x4 a0, a1;
;                     if (RES_BF16) { const u32x4 rw = __builtin_bit_cast(u32x4, r0[m][bj]); a0 = (f32x4){bf_lo(rw.x), bf_hi(rw.x), bf_lo(rw.y), bf_hi(rw.y)}; a1 = (f32x4){bf_lo(rw.z), bf_hi(rw.z), bf_lo(rw.w), bf_hi(rw.w)};
;                         if (RES_SCALE) { const float rf = rfac[row]; a0 = a0 * rf; a1 = a1 * rf; } }
;                     else { a0 = r0[m][bj]; a1 = r1[m][bj]; }
;                     const f32x4 v0 = acc[ai][bj][m][0] + a0, v1 = acc[ai][bj][m][1] + a1;
;                     u32x4 w; w.x = cvt_pk_bf16(v0[0], v0[1]); w.y = cvt_pk_bf16(v0[2], v0[3]); w.z = cvt_pk_bf16(v1[0], v1[1]); w.w = cvt_pk_bf16(v1[2], v1[3]); *(u32x4*)(ob + off + bj * HALF) = w;
;                     ss += (v0[0] * v0[0] + v0[1] * v0[1]) + (v0[2] * v0[2] + v0[3] * v0[3]) + (v1[0] * v1[0] + v1[1] * v1[1]) + (v1[2] * v1[2] + v1[3] * v1[3]);
;                     if (rowmax) mx = fmaxf(mx, fmaxf(fmaxf(fmaxf(fabsf(v0[0]), fabsf(v0[1])), fmaxf(fabsf(v0[2]), fabsf(v0[3]))), fmaxf(fmaxf(fabsf(v1[0]), fabsf(v1[1])), fmaxf(fabsf(v1[2]), fabsf(v1[3]))))); }
.LBB0_1364:
	s_nop 7
	v_lshl_add_u32 v245, s72, 8, v157
	v_mul_u32_u24_e32 v245, 0x2080, v245
	v_lshl_or_b32 v246, s73, 8, v159
	v_lshl_add_u32 v245, v246, 1, v245
	global_load_dwordx4 v[130:133], v245, s[100:101]
	global_load_dwordx4 v[134:137], v245, s[100:101] offset:256
	v_add_u32_e32 v246, 0x20800, v245
	global_load_dwordx4 v[142:145], v246, s[100:101]
	global_load_dwordx4 v[146:149], v246, s[100:101] offset:256
	v_add_u32_e32 v255, 0x41000, v245
	global_load_dwordx4 v[150:153], v255, s[100:101]
	global_load_dwordx4 v[166:169], v255, s[100:101] offset:256
	v_add_u32_e32 v246, 0x61800, v245
	global_load_dwordx4 v[170:173], v246, s[100:101]
	global_load_dwordx4 v[174:177], v246, s[100:101] offset:256
	v_add_u32_e32 v255, 0x104000, v245
	global_load_dwordx4 v[178:181], v255, s[100:101]
	global_load_dwordx4 v[182:185], v255, s[100:101] offset:256
	v_add_u32_e32 v246, 0x124800, v245
	global_load_dwordx4 v[186:189], v246, s[100:101]
	global_load_dwordx4 v[190:193], v246, s[100:101] offset:256
	v_add_u32_e32 v255, 0x145000, v245
	global_load_dwordx4 v[194:197], v255, s[100:101]
	global_load_dwordx4 v[198:201], v255, s[100:101] offset:256
	v_add_u32_e32 v246, 0x165800, v245
	global_load_dwordx4 v[202:205], v246, s[100:101]
	global_load_dwordx4 v[206:209], v246, s[100:101] offset:256
	s_waitcnt vmcnt(15)
	v_lshlrev_b32_e32 v248, 16, v130
	v_and_b32_e32 v249, 0xffff0000, v130
	v_lshlrev_b32_e32 v250, 16, v131
	v_and_b32_e32 v251, 0xffff0000, v131
	v_pk_add_f32 v[126:127], v[126:127], v[248:249]
	v_pk_add_f32 v[128:129], v[128:129], v[250:251]
	v_lshlrev_b32_e32 v248, 16, v132
	v_and_b32_e32 v249, 0xffff0000, v132
	v_lshlrev_b32_e32 v250, 16, v133
	v_and_b32_e32 v251, 0xffff0000, v133
	v_pk_add_f32 v[122:123], v[122:123], v[248:249]
	v_pk_add_f32 v[124:125], v[124:125], v[250:251]
	v_cvt_pk_bf16_f32 v130, v126, v127
	v_cvt_pk_bf16_f32 v131, v128, v129
	v_cvt_pk_bf16_f32 v132, v122, v123
	v_cvt_pk_bf16_f32 v133, v124, v125
	global_store_dwordx4 v245, v[130:133], s[98:99]
	v_mul_f32_e32 v247, v126, v126
	v_fmac_f32_e32 v247, v127, v127
	v_fmac_f32_e32 v247, v128, v128
	v_fmac_f32_e32 v247, v129, v129
	v_mul_f32_e32 v254, v122, v122
	v_fmac_f32_e32 v254, v123, v123
	v_fmac_f32_e32 v254, v124, v124
	v_fmac_f32_e32 v254, v125, v125
	s_waitcnt vmcnt(15)
	v_lshlrev_b32_e32 v248, 16, v134
	v_and_b32_e32 v249, 0xffff0000, v134
	v_lshlrev_b32_e32 v250, 16, v135
	v_and_b32_e32 v251, 0xffff0000, v135
	v_pk_add_f32 v[118:119], v[118:119], v[248:249]
	v_pk_add_f32 v[120:121], v[120:121], v[250:251]
	v_lshlrev_b32_e32 v248, 16, v136
	v_and_b32_e32 v249, 0xffff0000, v136
	v_lshlrev_b32_e32 v250, 16, v137
	v_and_b32_e32 v251, 0xffff0000, v137
	v_pk_add_f32 v[114:115], v[114:115], v[248:249]
	v_pk_add_f32 v[116:117], v[116:117], v[250:251]
	v_cvt_pk_bf16_f32 v134, v118, v119
	v_cvt_pk_bf16_f32 v135, v120, v121
	v_cvt_pk_bf16_f32 v136, v114, v115
	v_cvt_pk_bf16_f32 v137, v116, v117
	global_store_dwordx4 v245, v[134:137], s[98:99] offset:256
	v_fmac_f32_e32 v247, v118, v118
	v_fmac_f32_e32 v247, v119, v119
	v_fmac_f32_e32 v247, v120, v120
	v_fmac_f32_e32 v247, v121, v121
	v_fmac_f32_e32 v254, v114, v114
	v_fmac_f32_e32 v254, v115, v115
	v_fmac_f32_e32 v254, v116, v116
	v_fmac_f32_e32 v254, v117, v117
	v_add_f32_e32 v126, v247, v254
	s_waitcnt vmcnt(15)
	v_lshlrev_b32_e32 v248, 16, v142
	v_and_b32_e32 v249, 0xffff0000, v142
	v_lshlrev_b32_e32 v250, 16, v143
	v_and_b32_e32 v251, 0xffff0000, v143
	v_pk_add_f32 v[110:111], v[110:111], v[248:249]
	v_pk_add_f32 v[112:113], v[112:113], v[250:251]
	v_lshlrev_b32_e32 v248, 16, v144
	v_and_b32_e32 v249, 0xffff0000, v144
	v_lshlrev_b32_e32 v250, 16, v145
	v_and_b32_e32 v251, 0xffff0000, v145
	v_pk_add_f32 v[106:107], v[106:107], v[248:249]
	v_pk_add_f32 v[108:109], v[108:109], v[250:251]
	v_cvt_pk_bf16_f32 v142, v110, v111
	v_cvt_pk_bf16_f32 v143, v112, v113
	v_cvt_pk_bf16_f32 v144, v106, v107
	v_cvt_pk_bf16_f32 v145, v108, v109
	v_add_u32_e32 v246, 0x20800, v245
	global_store_dwordx4 v246, v[142:145], s[98:99]
	v_mul_f32_e32 v247, v110, v110
	v_fmac_f32_e32 v247, v111, v111
	v_fmac_f32_e32 v247, v112, v112
	v_fmac_f32_e32 v247, v113, v113
	v_mul_f32_e32 v254, v106, v106
	v_fmac_f32_e32 v254, v107, v107
	v_fmac_f32_e32 v254, v108, v108
	v_fmac_f32_e32 v254, v109, v109
	s_waitcnt vmcnt(15)
	v_lshlrev_b32_e32 v248, 16, v146
	v_and_b32_e32 v249, 0xffff0000, v146
	v_lshlrev_b32_e32 v250, 16, v147
	v_and_b32_e32 v251, 0xffff0000, v147
	v_pk_add_f32 v[102:103], v[102:103], v[248:249]
	v_pk_add_f32 v[104:105], v[104:105], v[250:251]
	v_lshlrev_b32_e32 v248, 16, v148
	v_and_b32_e32 v249, 0xffff0000, v148
	v_lshlrev_b32_e32 v250, 16, v149
	v_and_b32_e32 v251, 0xffff0000, v149
	v_pk_add_f32 v[98:99], v[98:99], v[248:249]
	v_pk_add_f32 v[100:101], v[100:101], v[250:251]
	v_cvt_pk_bf16_f32 v146, v102, v103
	v_cvt_pk_bf16_f32 v147, v104, v105
	v_cvt_pk_bf16_f32 v148, v98, v99
	v_cvt_pk_bf16_f32 v149, v100, v101
	v_add_u32_e32 v255, 0x20800, v245
	global_store_dwordx4 v255, v[146:149], s[98:99] offset:256
	v_fmac_f32_e32 v247, v102, v102
	v_fmac_f32_e32 v247, v103, v103
	v_fmac_f32_e32 v247, v104, v104
	v_fmac_f32_e32 v247, v105, v105
	v_fmac_f32_e32 v254, v98, v98
	v_fmac_f32_e32 v254, v99, v99
	v_fmac_f32_e32 v254, v100, v100
	v_fmac_f32_e32 v254, v101, v101
	v_add_f32_e32 v110, v247, v254
	s_waitcnt vmcnt(15)
; __device__ __forceinline__ unsigned cvt_pk_bf16(float lo, float hi) { unsigned r; asm volatile("v_cvt_pk_bf16_f32 %0, %1, %2" : "=v"(r) : "v"(lo), "v"(hi)); return r; }
; __device__ __forceinline__ float bf_lo(unsigned w) { return __uint_as_float(w << 16); }
; __device__ __forceinline__ float bf_hi(unsigned w) { return __uint_as_float(w & 0xffff0000u); }
;     __device__ __forceinline__ void operator()(EPI_ARGS) const {
;     ...
;                 for (int bj = 0; bj < 2; ++bj) { const size_t off = (size_t)(row0 + ai * HALF + m * 16) * ldc + col0 + bj * HALF;
;                     if (RES_BF16) { const u32x4 rw = *(const u32x4*)((const bf16*)resid + off); r0[m][bj] = __builtin_bit_cast(f32x4, rw); }
;                     else { r0[m][bj] = *(const f32x4*)((const float*)resid + off); r1[m][bj] = *(const f32x4*)((const float*)resid + off + 4); } }
; #pragma unroll
;             for (int m = 0; m < 4; ++m) { const int row = row0 + ai * HALF + m * 16; const size_t off = (size_t)row * ldc + col0; float ss = 0.f, mx = 0.f;
; #pragma unroll
;                 for (int bj = 0; bj < 2; ++bj) {
;                     f32x4 a0, a1;
;                     if (RES_BF16) { const u32x4 rw = __builtin_bit_cast(u32x4, r0[m][bj]); a0 = (f32x4){bf_lo(rw.x), bf_hi(rw.x), bf_lo(rw.y), bf_hi(rw.y)}; a1 = (f32x4){bf_lo(rw.z), bf_hi(rw.z), bf_lo(rw.w), bf_hi(rw.w)};
;                         if (RES_SCALE) { const float rf = rfac[row]; a0 = a0 * rf; a1 = a1 * rf; } }
;                     else { a0 = r0[m][bj]; a1 = r1[m][bj]; }
;                     const f32x4 v0 = acc[ai][bj][m][0] + a0, v1 = acc[ai][bj][m][1] + a1;
;                     u32x4 w; w.x = cvt_pk_bf16(v0[0], v0[1]); w.y = cvt_pk_bf16(v0[2], v0[3]); w.z = cvt_pk_bf16(v1[0], v1[1]); w.w = cvt_pk_bf16(v1[2], v1[3]); *(u32x4*)(ob + off + bj * HALF) = w;
;                     ss += (v0[0] * v0[0] + v0[1] * v0[1]) + (v0[2] * v0[2] + v0[3] * v0[3]) + (v1[0] * v1[0] + v1[1] * v1[1]) + (v1[2] * v1[2] + v1[3] * v1[3]);
;                     if (rowmax) mx = fmaxf(mx, fmaxf(fmaxf(fmaxf(fabsf(v0[0]), fabsf(v0[1])), fmaxf(fabsf(v0[2]), fabsf(v0[3]))), fmaxf(fmaxf(fabsf(v1[0]), fabsf(v1[1])), fmaxf(fabsf(v1[2]), fabsf(v1[3]))))); }
	v_lshlrev_b32_e32 v248, 16, v150
	v_and_b32_e32 v249, 0xffff0000, v150
	v_lshlrev_b32_e32 v250, 16, v151
	v_and_b32_e32 v251, 0xffff0000, v151
	v_pk_add_f32 v[94:95], v[94:95], v[248:249]
	v_pk_add_f32 v[96:97], v[96:97], v[250:251]
	v_lshlrev_b32_e32 v248, 16, v152
	v_and_b32_e32 v249, 0xffff0000, v152
	v_lshlrev_b32_e32 v250, 16, v153
	v_and_b32_e32 v251, 0xffff0000, v153
	v_pk_add_f32 v[90:91], v[90:91], v[248:249]
	v_pk_add_f32 v[92:93], v[92:93], v[250:251]
	v_cvt_pk_bf16_f32 v150, v94, v95
	v_cvt_pk_bf16_f32 v151, v96, v97
	v_cvt_pk_bf16_f32 v152, v90, v91
	v_cvt_pk_bf16_f32 v153, v92, v93
	v_add_u32_e32 v246, 0x41000, v245
	global_store_dwordx4 v246, v[150:153], s[98:99]
	v_mul_f32_e32 v247, v94, v94
	v_fmac_f32_e32 v247, v95, v95
	v_fmac_f32_e32 v247, v96, v96
	v_fmac_f32_e32 v247, v97, v97
	v_mul_f32_e32 v254, v90, v90
	v_fmac_f32_e32 v254, v91, v91
	v_fmac_f32_e32 v254, v92, v92
	v_fmac_f32_e32 v254, v93, v93
	s_waitcnt vmcnt(15)
	v_lshlrev_b32_e32 v248, 16, v166
	v_and_b32_e32 v249, 0xffff0000, v166
	v_lshlrev_b32_e32 v250, 16, v167
	v_and_b32_e32 v251, 0xffff0000, v167
	v_pk_add_f32 v[86:87], v[86:87], v[248:249]
	v_pk_add_f32 v[88:89], v[88:89], v[250:251]
	v_lshlrev_b32_e32 v248, 16, v168
	v_and_b32_e32 v249, 0xffff0000, v168
	v_lshlrev_b32_e32 v250, 16, v169
	v_and_b32_e32 v251, 0xffff0000, v169
	v_pk_add_f32 v[82:83], v[82:83], v[248:249]
	v_pk_add_f32 v[84:85], v[84:85], v[250:251]
	v_cvt_pk_bf16_f32 v166, v86, v87
	v_cvt_pk_bf16_f32 v167, v88, v89
	v_cvt_pk_bf16_f32 v168, v82, v83
	v_cvt_pk_bf16_f32 v169, v84, v85
	v_add_u32_e32 v255, 0x41000, v245
	global_store_dwordx4 v255, v[166:169], s[98:99] offset:256
	v_fmac_f32_e32 v247, v86, v86
	v_fmac_f32_e32 v247, v87, v87
	v_fmac_f32_e32 v247, v88, v88
	v_fmac_f32_e32 v247, v89, v89
	v_fmac_f32_e32 v254, v82, v82
	v_fmac_f32_e32 v254, v83, v83
	v_fmac_f32_e32 v254, v84, v84
	v_fmac_f32_e32 v254, v85, v85
	v_add_f32_e32 v94, v247, v254
	s_waitcnt vmcnt(15)
	v_lshlrev_b32_e32 v248, 16, v170
	v_and_b32_e32 v249, 0xffff0000, v170
	v_lshlrev_b32_e32 v250, 16, v171
	v_and_b32_e32 v251, 0xffff0000, v171
	v_pk_add_f32 v[78:79], v[78:79], v[248:249]
	v_pk_add_f32 v[80:81], v[80:81], v[250:251]
	v_lshlrev_b32_e32 v248, 16, v172
	v_and_b32_e32 v249, 0xffff0000, v172
	v_lshlrev_b32_e32 v250, 16, v173
	v_and_b32_e32 v251, 0xffff0000, v173
	v_pk_add_f32 v[74:75], v[74:75], v[248:249]
	v_pk_add_f32 v[76:77], v[76:77], v[250:251]
	v_cvt_pk_bf16_f32 v170, v78, v79
	v_cvt_pk_bf16_f32 v171, v80, v81
	v_cvt_pk_bf16_f32 v172, v74, v75
	v_cvt_pk_bf16_f32 v173, v76, v77
	v_add_u32_e32 v246, 0x61800, v245
	global_store_dwordx4 v246, v[170:173], s[98:99]
	v_mul_f32_e32 v247, v78, v78
	v_fmac_f32_e32 v247, v79, v79
	v_fmac_f32_e32 v247, v80, v80
	v_fmac_f32_e32 v247, v81, v81
	v_mul_f32_e32 v254, v74, v74
	v_fmac_f32_e32 v254, v75, v75
	v_fmac_f32_e32 v254, v76, v76
	v_fmac_f32_e32 v254, v77, v77
	s_waitcnt vmcnt(15)
	v_lshlrev_b32_e32 v248, 16, v174
	v_and_b32_e32 v249, 0xffff0000, v174
	v_lshlrev_b32_e32 v250, 16, v175
	v_and_b32_e32 v251, 0xffff0000, v175
	v_pk_add_f32 v[70:71], v[70:71], v[248:249]
	v_pk_add_f32 v[72:73], v[72:73], v[250:251]
	v_lshlrev_b32_e32 v248, 16, v176
	v_and_b32_e32 v249, 0xffff0000, v176
	v_lshlrev_b32_e32 v250, 16, v177
	v_and_b32_e32 v251, 0xffff0000, v177
	v_pk_add_f32 v[66:67], v[66:67], v[248:249]
	v_pk_add_f32 v[68:69], v[68:69], v[250:251]
	v_cvt_pk_bf16_f32 v174, v70, v71
	v_cvt_pk_bf16_f32 v175, v72, v73
	v_cvt_pk_bf16_f32 v176, v66, v67
	v_cvt_pk_bf16_f32 v177, v68, v69
	v_add_u32_e32 v255, 0x61800, v245
	global_store_dwordx4 v255, v[174:177], s[98:99] offset:256
	v_fmac_f32_e32 v247, v70, v70
	v_fmac_f32_e32 v247, v71, v71
	v_fmac_f32_e32 v247, v72, v72
	v_fmac_f32_e32 v247, v73, v73
	v_fmac_f32_e32 v254, v66, v66
	v_fmac_f32_e32 v254, v67, v67
	v_fmac_f32_e32 v254, v68, v68
	v_fmac_f32_e32 v254, v69, v69
	v_add_f32_e32 v78, v247, v254
	s_waitcnt vmcnt(15)
	v_lshlrev_b32_e32 v248, 16, v178
	v_and_b32_e32 v249, 0xffff0000, v178
	v_lshlrev_b32_e32 v250, 16, v179
	v_and_b32_e32 v251, 0xffff0000, v179
	v_pk_add_f32 v[62:63], v[62:63], v[248:249]
	v_pk_add_f32 v[64:65], v[64:65], v[250:251]
	v_lshlrev_b32_e32 v248, 16, v180
	v_and_b32_e32 v249, 0xffff0000, v180
	v_lshlrev_b32_e32 v250, 16, v181
	v_and_b32_e32 v251, 0xffff0000, v181
	v_pk_add_f32 v[58:59], v[58:59], v[248:249]
	v_pk_add_f32 v[60:61], v[60:61], v[250:251]
	v_cvt_pk_bf16_f32 v178, v62, v63
	v_cvt_pk_bf16_f32 v179, v64, v65
	v_cvt_pk_bf16_f32 v180, v58, v59
	v_cvt_pk_bf16_f32 v181, v60, v61
	v_add_u32_e32 v246, 0x104000, v245
	global_store_dwordx4 v246, v[178:181], s[98:99]
	v_mul_f32_e32 v247, v62, v62
	v_fmac_f32_e32 v247, v63, v63
	v_fmac_f32_e32 v247, v64, v64
	v_fmac_f32_e32 v247, v65, v65
	v_mul_f32_e32 v254, v58, v58
	v_fmac_f32_e32 v254, v59, v59
	v_fmac_f32_e32 v254, v60, v60
	v_fmac_f32_e32 v254, v61, v61
	s_waitcnt vmcnt(15)
	v_lshlrev_b32_e32 v248, 16, v182
	v_and_b32_e32 v249, 0xffff0000, v182
	v_lshlrev_b32_e32 v250, 16, v183
	v_and_b32_e32 v251, 0xffff0000, v183
	v_pk_add_f32 v[54:55], v[54:55], v[248:249]
	v_pk_add_f32 v[56:57], v[56:57], v[250:251]
	v_lshlrev_b32_e32 v248, 16, v184
	v_and_b32_e32 v249, 0xffff0000, v184
	v_lshlrev_b32_e32 v250, 16, v185
	v_and_b32_e32 v251, 0xffff0000, v185
	v_pk_add_f32 v[50:51], v[50:51], v[248:249]
	v_pk_add_f32 v[52:53], v[52:53], v[250:251]
	v_cvt_pk_bf16_f32 v182, v54, v55
	v_cvt_pk_bf16_f32 v183, v56, v57
	v_cvt_pk_bf16_f32 v184, v50, v51
	v_cvt_pk_bf16_f32 v185, v52, v53
	v_add_u32_e32 v255, 0x104000, v245
	global_store_dwordx4 v255, v[182:185], s[98:99] offset:256
	v_fmac_f32_e32 v247, v54, v54
	v_fmac_f32_e32 v247, v55, v55
	v_fmac_f32_e32 v247, v56, v56
	v_fmac_f32_e32 v247, v57, v57
	v_fmac_f32_e32 v254, v50, v50
	v_fmac_f32_e32 v254, v51, v51
	v_fmac_f32_e32 v254, v52, v52
	v_fmac_f32_e32 v254, v53, v53
	v_add_f32_e32 v62, v247, v254
	s_waitcnt vmcnt(15)
; __device__ __forceinline__ unsigned cvt_pk_bf16(float lo, float hi) { unsigned r; asm volatile("v_cvt_pk_bf16_f32 %0, %1, %2" : "=v"(r) : "v"(lo), "v"(hi)); return r; }
; __device__ __forceinline__ float bf_lo(unsigned w) { return __uint_as_float(w << 16); }
; __device__ __forceinline__ float bf_hi(unsigned w) { return __uint_as_float(w & 0xffff0000u); }
;     __device__ __forceinline__ void operator()(EPI_ARGS) const {
;     ...
;                 for (int bj = 0; bj < 2; ++bj) { const size_t off = (size_t)(row0 + ai * HALF + m * 16) * ldc + col0 + bj * HALF;
;                     if (RES_BF16) { const u32x4 rw = *(const u32x4*)((const bf16*)resid + off); r0[m][bj] = __builtin_bit_cast(f32x4, rw); }
;                     else { r0[m][bj] = *(const f32x4*)((const float*)resid + off); r1[m][bj] = *(const f32x4*)((const float*)resid + off + 4); } }
; #pragma unroll
;             for (int m = 0; m < 4; ++m) { const int row = row0 + ai * HALF + m * 16; const size_t off = (size_t)row * ldc + col0; float ss = 0.f, mx = 0.f;
; #pragma unroll
;                 for (int bj = 0; bj < 2; ++bj) {
;                     f32x4 a0, a1;
;                     if (RES_BF16) { const u32x4 rw = __builtin_bit_cast(u32x4, r0[m][bj]); a0 = (f32x4){bf_lo(rw.x), bf_hi(rw.x), bf_lo(rw.y), bf_hi(rw.y)}; a1 = (f32x4){bf_lo(rw.z), bf_hi(rw.z), bf_lo(rw.w), bf_hi(rw.w)};
;                         if (RES_SCALE) { const float rf = rfac[row]; a0 = a0 * rf; a1 = a1 * rf; } }
;                     else { a0 = r0[m][bj]; a1 = r1[m][bj]; }
;                     const f32x4 v0 = acc[ai][bj][m][0] + a0, v1 = acc[ai][bj][m][1] + a1;
;                     u32x4 w; w.x = cvt_pk_bf16(v0[0], v0[1]); w.y = cvt_pk_bf16(v0[2], v0[3]); w.z = cvt_pk_bf16(v1[0], v1[1]); w.w = cvt_pk_bf16(v1[2], v1[3]); *(u32x4*)(ob + off + bj * HALF) = w;
;                     ss += (v0[0] * v0[0] + v0[1] * v0[1]) + (v0[2] * v0[2] + v0[3] * v0[3]) + (v1[0] * v1[0] + v1[1] * v1[1]) + (v1[2] * v1[2] + v1[3] * v1[3]);
;                     if (rowmax) mx = fmaxf(mx, fmaxf(fmaxf(fmaxf(fabsf(v0[0]), fabsf(v0[1])), fmaxf(fabsf(v0[2]), fabsf(v0[3]))), fmaxf(fmaxf(fabsf(v1[0]), fabsf(v1[1])), fmaxf(fabsf(v1[2]), fabsf(v1[3]))))); }
	v_lshlrev_b32_e32 v248, 16, v186
	v_and_b32_e32 v249, 0xffff0000, v186
	v_lshlrev_b32_e32 v250, 16, v187
	v_and_b32_e32 v251, 0xffff0000, v187
	v_pk_add_f32 v[46:47], v[46:47], v[248:249]
	v_pk_add_f32 v[48:49], v[48:49], v[250:251]
	v_lshlrev_b32_e32 v248, 16, v188
	v_and_b32_e32 v249, 0xffff0000, v188
	v_lshlrev_b32_e32 v250, 16, v189
	v_and_b32_e32 v251, 0xffff0000, v189
	v_pk_add_f32 v[42:43], v[42:43], v[248:249]
	v_pk_add_f32 v[44:45], v[44:45], v[250:251]
	v_cvt_pk_bf16_f32 v186, v46, v47
	v_cvt_pk_bf16_f32 v187, v48, v49
	v_cvt_pk_bf16_f32 v188, v42, v43
	v_cvt_pk_bf16_f32 v189, v44, v45
	v_add_u32_e32 v246, 0x124800, v245
	global_store_dwordx4 v246, v[186:189], s[98:99]
	v_mul_f32_e32 v247, v46, v46
	v_fmac_f32_e32 v247, v47, v47
	v_fmac_f32_e32 v247, v48, v48
	v_fmac_f32_e32 v247, v49, v49
	v_mul_f32_e32 v254, v42, v42
	v_fmac_f32_e32 v254, v43, v43
	v_fmac_f32_e32 v254, v44, v44
	v_fmac_f32_e32 v254, v45, v45
	s_waitcnt vmcnt(15)
	v_lshlrev_b32_e32 v248, 16, v190
	v_and_b32_e32 v249, 0xffff0000, v190
	v_lshlrev_b32_e32 v250, 16, v191
	v_and_b32_e32 v251, 0xffff0000, v191
	v_pk_add_f32 v[38:39], v[38:39], v[248:249]
	v_pk_add_f32 v[40:41], v[40:41], v[250:251]
	v_lshlrev_b32_e32 v248, 16, v192
	v_and_b32_e32 v249, 0xffff0000, v192
	v_lshlrev_b32_e32 v250, 16, v193
	v_and_b32_e32 v251, 0xffff0000, v193
	v_pk_add_f32 v[34:35], v[34:35], v[248:249]
	v_pk_add_f32 v[36:37], v[36:37], v[250:251]
	v_cvt_pk_bf16_f32 v190, v38, v39
	v_cvt_pk_bf16_f32 v191, v40, v41
	v_cvt_pk_bf16_f32 v192, v34, v35
	v_cvt_pk_bf16_f32 v193, v36, v37
	v_add_u32_e32 v255, 0x124800, v245
	global_store_dwordx4 v255, v[190:193], s[98:99] offset:256
	v_fmac_f32_e32 v247, v38, v38
	v_fmac_f32_e32 v247, v39, v39
	v_fmac_f32_e32 v247, v40, v40
	v_fmac_f32_e32 v247, v41, v41
	v_fmac_f32_e32 v254, v34, v34
	v_fmac_f32_e32 v254, v35, v35
	v_fmac_f32_e32 v254, v36, v36
	v_fmac_f32_e32 v254, v37, v37
	v_add_f32_e32 v46, v247, v254
	s_waitcnt vmcnt(15)
	v_lshlrev_b32_e32 v248, 16, v194
	v_and_b32_e32 v249, 0xffff0000, v194
	v_lshlrev_b32_e32 v250, 16, v195
	v_and_b32_e32 v251, 0xffff0000, v195
	v_pk_add_f32 v[30:31], v[30:31], v[248:249]
	v_pk_add_f32 v[32:33], v[32:33], v[250:251]
	v_lshlrev_b32_e32 v248, 16, v196
	v_and_b32_e32 v249, 0xffff0000, v196
	v_lshlrev_b32_e32 v250, 16, v197
	v_and_b32_e32 v251, 0xffff0000, v197
	v_pk_add_f32 v[26:27], v[26:27], v[248:249]
	v_pk_add_f32 v[28:29], v[28:29], v[250:251]
	v_cvt_pk_bf16_f32 v194, v30, v31
	v_cvt_pk_bf16_f32 v195, v32, v33
	v_cvt_pk_bf16_f32 v196, v26, v27
	v_cvt_pk_bf16_f32 v197, v28, v29
	v_add_u32_e32 v246, 0x145000, v245
	global_store_dwordx4 v246, v[194:197], s[98:99]
	v_mul_f32_e32 v247, v30, v30
	v_fmac_f32_e32 v247, v31, v31
	v_fmac_f32_e32 v247, v32, v32
	v_fmac_f32_e32 v247, v33, v33
	v_mul_f32_e32 v254, v26, v26
	v_fmac_f32_e32 v254, v27, v27
	v_fmac_f32_e32 v254, v28, v28
	v_fmac_f32_e32 v254, v29, v29
	s_waitcnt vmcnt(15)
	v_lshlrev_b32_e32 v248, 16, v198
	v_and_b32_e32 v249, 0xffff0000, v198
	v_lshlrev_b32_e32 v250, 16, v199
	v_and_b32_e32 v251, 0xffff0000, v199
	v_pk_add_f32 v[22:23], v[22:23], v[248:249]
	v_pk_add_f32 v[24:25], v[24:25], v[250:251]
	v_lshlrev_b32_e32 v248, 16, v200
	v_and_b32_e32 v249, 0xffff0000, v200
	v_lshlrev_b32_e32 v250, 16, v201
	v_and_b32_e32 v251, 0xffff0000, v201
	v_pk_add_f32 v[18:19], v[18:19], v[248:249]
	v_pk_add_f32 v[20:21], v[20:21], v[250:251]
	v_cvt_pk_bf16_f32 v198, v22, v23
	v_cvt_pk_bf16_f32 v199, v24, v25
	v_cvt_pk_bf16_f32 v200, v18, v19
	v_cvt_pk_bf16_f32 v201, v20, v21
	v_add_u32_e32 v255, 0x145000, v245
	global_store_dwordx4 v255, v[198:201], s[98:99] offset:256
	v_fmac_f32_e32 v247, v22, v22
	v_fmac_f32_e32 v247, v23, v23
	v_fmac_f32_e32 v247, v24, v24
	v_fmac_f32_e32 v247, v25, v25
	v_fmac_f32_e32 v254, v18, v18
	v_fmac_f32_e32 v254, v19, v19
	v_fmac_f32_e32 v254, v20, v20
	v_fmac_f32_e32 v254, v21, v21
	v_add_f32_e32 v30, v247, v254
	s_waitcnt vmcnt(15)
;     __device__ __forceinline__ void operator()(EPI_ARGS) const {
;     ...
;                 ss += __shfl_xor(ss, 16); ss += __shfl_xor(ss, 32); ssv[ai * 4 + m] = ss;
;                 if (rowmax) { mx = fmaxf(mx, __shfl_xor(mx, 16)); mx = fmaxf(mx, __shfl_xor(mx, 32)); } mxv[ai * 4 + m] = mx; }
;             asm volatile("" ::: "memory"); }
;         float s0 = 0.f, s1 = 0.f, m0 = 0.f, m1 = 0.f;
; #pragma unroll
;         for (int k = 0; k < 8; ++k) if ((k >> 1) == fq) { if (k & 1) { s1 = ssv[k]; m1 = mxv[k]; } else { s0 = ssv[k]; m0 = mxv[k]; } }
;         const int rq = row0 + (fq >> 1) * HALF + (fq & 1) * 32;
;         __hip_atomic_fetch_add(rowsq + rq, s0, __ATOMIC_RELAXED, __HIP_MEMORY_SCOPE_AGENT); __hip_atomic_fetch_add(rowsq + rq + 16, s1, __ATOMIC_RELAXED, __HIP_MEMORY_SCOPE_AGENT);
	v_lshlrev_b32_e32 v248, 16, v202
	v_and_b32_e32 v249, 0xffff0000, v202
	v_lshlrev_b32_e32 v250, 16, v203
	v_and_b32_e32 v251, 0xffff0000, v203
	v_pk_add_f32 v[14:15], v[14:15], v[248:249]
	v_pk_add_f32 v[16:17], v[16:17], v[250:251]
	v_lshlrev_b32_e32 v248, 16, v204
	v_and_b32_e32 v249, 0xffff0000, v204
	v_lshlrev_b32_e32 v250, 16, v205
	v_and_b32_e32 v251, 0xffff0000, v205
	v_pk_add_f32 v[10:11], v[10:11], v[248:249]
	v_pk_add_f32 v[12:13], v[12:13], v[250:251]
	v_cvt_pk_bf16_f32 v202, v14, v15
	v_cvt_pk_bf16_f32 v203, v16, v17
	v_cvt_pk_bf16_f32 v204, v10, v11
	v_cvt_pk_bf16_f32 v205, v12, v13
	v_add_u32_e32 v246, 0x165800, v245
	global_store_dwordx4 v246, v[202:205], s[98:99]
	v_mul_f32_e32 v247, v14, v14
	v_fmac_f32_e32 v247, v15, v15
	v_fmac_f32_e32 v247, v16, v16
	v_fmac_f32_e32 v247, v17, v17
	v_mul_f32_e32 v254, v10, v10
	v_fmac_f32_e32 v254, v11, v11
	v_fmac_f32_e32 v254, v12, v12
	v_fmac_f32_e32 v254, v13, v13
	s_waitcnt vmcnt(15)
	v_lshlrev_b32_e32 v248, 16, v206
	v_and_b32_e32 v249, 0xffff0000, v206
	v_lshlrev_b32_e32 v250, 16, v207
	v_and_b32_e32 v251, 0xffff0000, v207
	v_pk_add_f32 v[6:7], v[6:7], v[248:249]
	v_pk_add_f32 v[8:9], v[8:9], v[250:251]
	v_lshlrev_b32_e32 v248, 16, v208
	v_and_b32_e32 v249, 0xffff0000, v208
	v_lshlrev_b32_e32 v250, 16, v209
	v_and_b32_e32 v251, 0xffff0000, v209
	v_pk_add_f32 v[2:3], v[2:3], v[248:249]
	v_pk_add_f32 v[4:5], v[4:5], v[250:251]
	v_cvt_pk_bf16_f32 v206, v6, v7
	v_cvt_pk_bf16_f32 v207, v8, v9
	v_cvt_pk_bf16_f32 v208, v2, v3
	v_cvt_pk_bf16_f32 v209, v4, v5
	v_add_u32_e32 v255, 0x165800, v245
	global_store_dwordx4 v255, v[206:209], s[98:99] offset:256
	v_fmac_f32_e32 v247, v6, v6
	v_fmac_f32_e32 v247, v7, v7
	v_fmac_f32_e32 v247, v8, v8
	v_fmac_f32_e32 v247, v9, v9
	v_fmac_f32_e32 v254, v2, v2
	v_fmac_f32_e32 v254, v3, v3
	v_fmac_f32_e32 v254, v4, v4
	v_fmac_f32_e32 v254, v5, v5
	v_add_f32_e32 v14, v247, v254
	v_and_b32_e32 v255, 63, v0
	v_xor_b32_e32 v252, 16, v255
	v_xor_b32_e32 v253, 32, v255
	v_lshlrev_b32_e32 v252, 2, v252
	v_lshlrev_b32_e32 v253, 2, v253
	ds_bpermute_b32 v127, v252, v126
	ds_bpermute_b32 v111, v252, v110
	ds_bpermute_b32 v95, v252, v94
	ds_bpermute_b32 v79, v252, v78
	ds_bpermute_b32 v63, v252, v62
	ds_bpermute_b32 v47, v252, v46
	ds_bpermute_b32 v31, v252, v30
	ds_bpermute_b32 v15, v252, v14
	s_waitcnt lgkmcnt(0)
	v_add_f32_e32 v126, v126, v127
	v_add_f32_e32 v110, v110, v111
	v_add_f32_e32 v94, v94, v95
	v_add_f32_e32 v78, v78, v79
	v_add_f32_e32 v62, v62, v63
	v_add_f32_e32 v46, v46, v47
	v_add_f32_e32 v30, v30, v31
	v_add_f32_e32 v14, v14, v15
	ds_bpermute_b32 v127, v253, v126
	ds_bpermute_b32 v111, v253, v110
	ds_bpermute_b32 v95, v253, v94
	ds_bpermute_b32 v79, v253, v78
	ds_bpermute_b32 v63, v253, v62
	ds_bpermute_b32 v47, v253, v46
	ds_bpermute_b32 v31, v253, v30
	ds_bpermute_b32 v15, v253, v14
	s_waitcnt lgkmcnt(0)
	v_add_f32_e32 v126, v126, v127
	v_add_f32_e32 v110, v110, v111
	v_add_f32_e32 v94, v94, v95
	v_add_f32_e32 v78, v78, v79
	v_add_f32_e32 v62, v62, v63
	v_add_f32_e32 v46, v46, v47
	v_add_f32_e32 v30, v30, v31
	v_add_f32_e32 v14, v14, v15
	v_cndmask_b32_e64 v248, 0, v126, s[2:3]
	v_cndmask_b32_e64 v249, 0, v110, s[2:3]
	v_cndmask_b32_e64 v248, v248, v94, s[4:5]
	v_cndmask_b32_e64 v249, v249, v78, s[4:5]
	v_cndmask_b32_e64 v248, v248, v62, s[6:7]
	v_cndmask_b32_e64 v249, v249, v46, s[6:7]
	v_cndmask_b32_e64 v248, v248, v30, s[8:9]
	v_cndmask_b32_e64 v249, v249, v14, s[8:9]
	v_lshl_add_u32 v250, s72, 8, v157
	v_add_u32_e32 v250, v158, v250
	v_lshlrev_b32_e32 v250, 2, v250
	global_atomic_add_f32 v250, v248, s[34:35]
	global_atomic_add_f32 v250, v249, s[34:35] offset:64
	s_and_b64 vcc, exec, s[10:11]
	s_mov_b64 s[10:11], -1
	s_cbranch_vccnz .LBB0_1349
	s_andn2_b64 vcc, exec, s[0:1]
	s_cbranch_vccnz .LBB0_1348
	s_barrier
	s_branch .LBB0_1348

; __global__ void __launch_bounds__(NWAVES * 64, 2) fwd_kernel(Args args) {
	.amdhsa_kernel _Z10fwd_kernel4Args
		.amdhsa_group_segment_fixed_size 0
		.amdhsa_private_segment_fixed_size 0
		.amdhsa_kernarg_size 456
		.amdhsa_user_sgpr_count 2
		.amdhsa_user_sgpr_dispatch_ptr 0
		.amdhsa_user_sgpr_queue_ptr 0
		.amdhsa_user_sgpr_kernarg_segment_ptr 1
		.amdhsa_user_sgpr_dispatch_id 0
		.amdhsa_user_sgpr_kernarg_preload_length 0
		.amdhsa_user_sgpr_kernarg_preload_offset 0
		.amdhsa_user_sgpr_private_segment_size 0
		.amdhsa_uses_dynamic_stack 0
		.amdhsa_enable_private_segment 0
		.amdhsa_system_sgpr_workgroup_id_x 1
		.amdhsa_system_sgpr_workgroup_id_y 0
		.amdhsa_system_sgpr_workgroup_id_z 0
		.amdhsa_system_sgpr_workgroup_info 0
		.amdhsa_system_vgpr_workitem_id 0
		.amdhsa_next_free_vgpr 256
		.amdhsa_next_free_sgpr 102
		.amdhsa_accum_offset 256
		.amdhsa_reserve_vcc 1
		.amdhsa_float_round_mode_32 0
		.amdhsa_float_round_mode_16_64 0
		.amdhsa_float_denorm_mode_32 3
		.amdhsa_float_denorm_mode_16_64 3
		.amdhsa_dx10_clamp 1
		.amdhsa_ieee_mode 1
		.amdhsa_fp16_overflow 0
		.amdhsa_tg_split 0
		.amdhsa_exception_fp_ieee_invalid_op 0
		.amdhsa_exception_fp_denorm_src 0
		.amdhsa_exception_fp_ieee_div_zero 0
		.amdhsa_exception_fp_ieee_overflow 0
		.amdhsa_exception_fp_ieee_underflow 0
		.amdhsa_exception_fp_ieee_inexact 0
		.amdhsa_exception_int_div_zero 0
	.end_amdhsa_kernel

; __global__ void __launch_bounds__(NWAVES * 64, 2) fwd_kernel(Args args) {
amdhsa.kernels:
  - .agpr_count:     0
    .args:
      - .offset:         0
        .size:           200
        .value_kind:     by_value
      - .offset:         200
        .size:           4
        .value_kind:     hidden_block_count_x
      - .offset:         204
        .size:           4
        .value_kind:     hidden_block_count_y
      - .offset:         208
        .size:           4
        .value_kind:     hidden_block_count_z
      - .offset:         212
        .size:           2
        .value_kind:     hidden_group_size_x
      - .offset:         214
        .size:           2
        .value_kind:     hidden_group_size_y
      - .offset:         216
        .size:           2
        .value_kind:     hidden_group_size_z
      - .offset:         218
        .size:           2
        .value_kind:     hidden_remainder_x
      - .offset:         220
        .size:           2
        .value_kind:     hidden_remainder_y
      - .offset:         222
        .size:           2
        .value_kind:     hidden_remainder_z
      - .offset:         240
        .size:           8
        .value_kind:     hidden_global_offset_x
      - .offset:         248
        .size:           8
        .value_kind:     hidden_global_offset_y
      - .offset:         256
        .size:           8
        .value_kind:     hidden_global_offset_z
      - .offset:         264
        .size:           2
        .value_kind:     hidden_grid_dims
      - .offset:         320
        .size:           4
        .value_kind:     hidden_dynamic_lds_size
    .group_segment_fixed_size: 0
    .kernarg_segment_align: 8
    .kernarg_segment_size: 456
    .language:       OpenCL C
    .language_version:
      - 2
      - 0
    .max_flat_workgroup_size: 512
    .name:           _Z10fwd_kernel4Args
    .private_segment_fixed_size: 0
    .sgpr_count:     108
    .sgpr_spill_count: 63
    .symbol:         _Z10fwd_kernel4Args.kd
    .uniform_work_group_size: 1
    .uses_dynamic_stack: false
    .vgpr_count:     256
    .vgpr_spill_count: 0
    .wavefront_size: 64
